# G1 and UP epilogue stores made write-through (sc1) so the grid barrier's L2 writeback is short
# speedup vs baseline: 1.0131x; 1.0103x over previous
.LBB0_136:
	s_lshl_b32 s0, s98, 8
	v_mov_b32_e32 v1, v192
	v_mov_b32_e32 v2, v169
	s_add_i32 s0, s0, s82
	s_and_b64 vcc, exec, s[36:37]
	v_add_u32_e32 v182, s0, v1
	s_lshl_b32 s0, s97, 8
	s_or_b32 s0, s0, s83
	v_lshl_add_u32 v2, v2, 3, s0
	v_ashrrev_i32_e32 v3, 31, v2
	v_lshlrev_b64 v[2:3], 1, v[2:3]
	v_ashrrev_i32_e32 v183, 31, v182
	v_lshl_add_u64 v[184:185], s[10:11], 0, v[2:3]
	v_lshlrev_b64 v[132:133], 12, v[182:183]
	v_lshl_add_u64 v[132:133], v[184:185], 0, v[132:133]
	global_load_dwordx4 v[196:199], v[132:133], off
	global_load_dwordx4 v[208:211], v[132:133], off offset:256
	v_add_u32_e32 v190, 16, v182
	v_ashrrev_i32_e32 v191, 31, v190
	v_lshlrev_b64 v[132:133], 12, v[190:191]
	v_lshl_add_u64 v[132:133], v[184:185], 0, v[132:133]
	global_load_dwordx4 v[152:155], v[132:133], off
	global_load_dwordx4 v[148:151], v[132:133], off offset:256
	v_add_u32_e32 v188, 32, v182
	v_ashrrev_i32_e32 v189, 31, v188
	v_lshlrev_b64 v[132:133], 12, v[188:189]
	v_lshl_add_u64 v[132:133], v[184:185], 0, v[132:133]
	global_load_dwordx4 v[144:147], v[132:133], off
	global_load_dwordx4 v[140:143], v[132:133], off offset:256
	v_add_u32_e32 v186, 48, v182
	v_ashrrev_i32_e32 v187, 31, v186
	v_lshlrev_b64 v[132:133], 12, v[186:187]
	v_lshl_add_u64 v[132:133], v[184:185], 0, v[132:133]
	global_load_dwordx4 v[136:139], v[132:133], off
	s_nop 0
	global_load_dwordx4 v[132:135], v[132:133], off offset:256
	v_lshlrev_b64 v[212:213], 11, v[182:183]
	s_mov_b64 s[0:1], -1
	s_waitcnt vmcnt(0)
	v_lshlrev_b32_e32 v214, 16, v196
	v_and_b32_e32 v215, 0xffff0000, v196
	v_lshlrev_b32_e32 v196, 16, v197
	v_and_b32_e32 v197, 0xffff0000, v197
	v_lshlrev_b32_e32 v216, 16, v198
	v_and_b32_e32 v217, 0xffff0000, v198
	v_lshlrev_b32_e32 v198, 16, v199
	v_and_b32_e32 v199, 0xffff0000, v199
	v_pk_mul_f32 v[126:127], v[126:127], v[196:197]
	v_pk_mul_f32 v[124:125], v[124:125], v[214:215]
	v_pk_mul_f32 v[128:129], v[128:129], v[216:217]
	v_pk_mul_f32 v[130:131], v[130:131], v[198:199]
	v_cvt_pk_bf16_f32 v124, v124, v125
	v_cvt_pk_bf16_f32 v125, v126, v127
	v_cvt_pk_bf16_f32 v126, v128, v129
	v_lshl_add_u64 v[128:129], s[6:7], 0, v[212:213]
	v_cvt_pk_bf16_f32 v127, v130, v131
	v_lshl_add_u64 v[128:129], v[128:129], 0, v[2:3]
	global_store_dwordx4 v[128:129], v[124:127], off sc1
	v_lshlrev_b32_e32 v130, 16, v210
	v_and_b32_e32 v131, 0xffff0000, v210
	v_lshlrev_b32_e32 v124, 16, v208
	v_and_b32_e32 v125, 0xffff0000, v208
	v_lshlrev_b32_e32 v126, 16, v209
	v_and_b32_e32 v127, 0xffff0000, v209
	v_lshlrev_b32_e32 v196, 16, v211
	v_and_b32_e32 v197, 0xffff0000, v211
	v_pk_mul_f32 v[118:119], v[118:119], v[126:127]
	v_pk_mul_f32 v[116:117], v[116:117], v[124:125]
	v_pk_mul_f32 v[122:123], v[122:123], v[196:197]
	v_pk_mul_f32 v[120:121], v[120:121], v[130:131]
	v_cvt_pk_bf16_f32 v116, v116, v117
	v_cvt_pk_bf16_f32 v117, v118, v119
	v_cvt_pk_bf16_f32 v118, v120, v121
	v_cvt_pk_bf16_f32 v119, v122, v123
	global_store_dwordx4 v[128:129], v[116:119], off offset:256 sc1
	v_lshlrev_b32_e32 v120, 16, v153
	v_and_b32_e32 v121, 0xffff0000, v153
	v_lshlrev_b32_e32 v118, 16, v152
	v_and_b32_e32 v119, 0xffff0000, v152
	v_lshlrev_b32_e32 v122, 16, v154
	v_and_b32_e32 v123, 0xffff0000, v154
	v_lshlrev_b64 v[116:117], 11, v[190:191]
	v_lshlrev_b32_e32 v124, 16, v155
	v_and_b32_e32 v125, 0xffff0000, v155
	v_pk_mul_f32 v[110:111], v[110:111], v[120:121]
	v_pk_mul_f32 v[108:109], v[108:109], v[118:119]
	v_pk_mul_f32 v[112:113], v[112:113], v[122:123]
	v_pk_mul_f32 v[114:115], v[114:115], v[124:125]
	v_cvt_pk_bf16_f32 v108, v108, v109
	v_cvt_pk_bf16_f32 v109, v110, v111
	v_cvt_pk_bf16_f32 v110, v112, v113
	v_lshl_add_u64 v[112:113], s[6:7], 0, v[116:117]
	v_cvt_pk_bf16_f32 v111, v114, v115
	v_lshl_add_u64 v[112:113], v[112:113], 0, v[2:3]
	global_store_dwordx4 v[112:113], v[108:111], off sc1
	v_lshlrev_b32_e32 v114, 16, v150
	v_and_b32_e32 v115, 0xffff0000, v150
	v_lshlrev_b32_e32 v108, 16, v148
	v_and_b32_e32 v109, 0xffff0000, v148
	v_lshlrev_b32_e32 v110, 16, v149
	v_and_b32_e32 v111, 0xffff0000, v149
	v_lshlrev_b32_e32 v116, 16, v151
	v_and_b32_e32 v117, 0xffff0000, v151
	v_pk_mul_f32 v[106:107], v[106:107], v[110:111]
	v_pk_mul_f32 v[104:105], v[104:105], v[108:109]
	v_pk_mul_f32 v[108:109], v[102:103], v[116:117]
	v_pk_mul_f32 v[102:103], v[100:101], v[114:115]
	v_cvt_pk_bf16_f32 v100, v104, v105
	v_cvt_pk_bf16_f32 v101, v106, v107
	v_cvt_pk_bf16_f32 v102, v102, v103
	v_cvt_pk_bf16_f32 v103, v108, v109
	global_store_dwordx4 v[112:113], v[100:103], off offset:256 sc1
	v_lshlrev_b32_e32 v104, 16, v145
	v_and_b32_e32 v105, 0xffff0000, v145
	v_lshlrev_b32_e32 v102, 16, v144
	v_and_b32_e32 v103, 0xffff0000, v144
	v_lshlrev_b64 v[100:101], 11, v[188:189]
	v_lshlrev_b32_e32 v106, 16, v146
	v_and_b32_e32 v107, 0xffff0000, v146
	v_lshlrev_b32_e32 v108, 16, v147
	v_and_b32_e32 v109, 0xffff0000, v147
	v_pk_mul_f32 v[96:97], v[96:97], v[102:103]
	v_pk_mul_f32 v[98:99], v[98:99], v[104:105]
	v_pk_mul_f32 v[102:103], v[94:95], v[108:109]
	v_pk_mul_f32 v[94:95], v[92:93], v[106:107]
	v_cvt_pk_bf16_f32 v92, v96, v97
	v_lshl_add_u64 v[96:97], s[6:7], 0, v[100:101]
	v_cvt_pk_bf16_f32 v93, v98, v99
	v_cvt_pk_bf16_f32 v94, v94, v95
	v_cvt_pk_bf16_f32 v95, v102, v103
	v_lshl_add_u64 v[96:97], v[96:97], 0, v[2:3]
	global_store_dwordx4 v[96:97], v[92:95], off sc1
	v_lshlrev_b32_e32 v98, 16, v142
	v_and_b32_e32 v99, 0xffff0000, v142
	v_lshlrev_b32_e32 v92, 16, v140
	v_and_b32_e32 v93, 0xffff0000, v140
	v_lshlrev_b32_e32 v94, 16, v141
	v_and_b32_e32 v95, 0xffff0000, v141
	v_lshlrev_b32_e32 v100, 16, v143
	v_and_b32_e32 v101, 0xffff0000, v143
	v_pk_mul_f32 v[90:91], v[90:91], v[94:95]
	v_pk_mul_f32 v[88:89], v[88:89], v[92:93]
	v_pk_mul_f32 v[92:93], v[86:87], v[100:101]
	v_pk_mul_f32 v[86:87], v[84:85], v[98:99]
	v_cvt_pk_bf16_f32 v84, v88, v89
	v_cvt_pk_bf16_f32 v85, v90, v91
	v_cvt_pk_bf16_f32 v86, v86, v87
	v_cvt_pk_bf16_f32 v87, v92, v93
	global_store_dwordx4 v[96:97], v[84:87], off offset:256 sc1
	v_lshlrev_b32_e32 v88, 16, v137
	v_and_b32_e32 v89, 0xffff0000, v137
	v_lshlrev_b32_e32 v86, 16, v136
	v_and_b32_e32 v87, 0xffff0000, v136
	v_lshlrev_b64 v[84:85], 11, v[186:187]
	v_lshlrev_b32_e32 v90, 16, v138
	v_and_b32_e32 v91, 0xffff0000, v138
	v_lshlrev_b32_e32 v92, 16, v139
	v_and_b32_e32 v93, 0xffff0000, v139
	v_pk_mul_f32 v[80:81], v[80:81], v[86:87]
	v_pk_mul_f32 v[82:83], v[82:83], v[88:89]
	v_pk_mul_f32 v[86:87], v[78:79], v[92:93]
	v_pk_mul_f32 v[78:79], v[76:77], v[90:91]
	v_cvt_pk_bf16_f32 v76, v80, v81
	v_lshl_add_u64 v[80:81], s[6:7], 0, v[84:85]
	v_cvt_pk_bf16_f32 v77, v82, v83
	v_cvt_pk_bf16_f32 v78, v78, v79
	v_cvt_pk_bf16_f32 v79, v86, v87
	v_lshl_add_u64 v[80:81], v[80:81], 0, v[2:3]
	global_store_dwordx4 v[80:81], v[76:79], off sc1
	v_lshlrev_b32_e32 v82, 16, v134
	v_and_b32_e32 v83, 0xffff0000, v134
	v_lshlrev_b32_e32 v76, 16, v132
	v_and_b32_e32 v77, 0xffff0000, v132
	v_lshlrev_b32_e32 v78, 16, v133
	v_and_b32_e32 v79, 0xffff0000, v133
	v_lshlrev_b32_e32 v84, 16, v135
	v_and_b32_e32 v85, 0xffff0000, v135
	v_pk_mul_f32 v[74:75], v[74:75], v[78:79]
	v_pk_mul_f32 v[72:73], v[72:73], v[76:77]
	v_pk_mul_f32 v[76:77], v[70:71], v[84:85]
	v_pk_mul_f32 v[70:71], v[68:69], v[82:83]
	v_add_u32_e32 v100, 0x80, v182
	v_cvt_pk_bf16_f32 v68, v72, v73
	v_cvt_pk_bf16_f32 v69, v74, v75
	v_cvt_pk_bf16_f32 v70, v70, v71
	v_cvt_pk_bf16_f32 v71, v76, v77
	v_ashrrev_i32_e32 v101, 31, v100
	global_store_dwordx4 v[80:81], v[68:71], off offset:256 sc1
	v_add_u32_e32 v102, 0x90, v182
	v_ashrrev_i32_e32 v103, 31, v102
	v_lshlrev_b64 v[68:69], 12, v[100:101]
	v_lshl_add_u64 v[68:69], v[184:185], 0, v[68:69]
	global_load_dwordx4 v[72:75], v[68:69], off
	global_load_dwordx4 v[76:79], v[68:69], off offset:256
	v_lshlrev_b64 v[68:69], 12, v[102:103]
	v_lshl_add_u64 v[68:69], v[184:185], 0, v[68:69]
	global_load_dwordx4 v[80:83], v[68:69], off
	global_load_dwordx4 v[84:87], v[68:69], off offset:256
	v_add_u32_e32 v104, 0xa0, v182
	v_ashrrev_i32_e32 v105, 31, v104
	v_lshlrev_b64 v[68:69], 12, v[104:105]
	v_lshl_add_u64 v[68:69], v[184:185], 0, v[68:69]
	global_load_dwordx4 v[88:91], v[68:69], off
	global_load_dwordx4 v[92:95], v[68:69], off offset:256
	v_add_u32_e32 v106, 0xb0, v182
	v_ashrrev_i32_e32 v107, 31, v106
	v_lshlrev_b64 v[68:69], 12, v[106:107]
	v_lshl_add_u64 v[68:69], v[184:185], 0, v[68:69]
	global_load_dwordx4 v[96:99], v[68:69], off
	s_nop 0
	global_load_dwordx4 v[68:71], v[68:69], off offset:256
	v_lshlrev_b64 v[100:101], 11, v[100:101]
	s_waitcnt vmcnt(0)
	v_lshlrev_b32_e32 v108, 16, v72
	v_and_b32_e32 v109, 0xffff0000, v72
	v_lshlrev_b32_e32 v72, 16, v73
	v_and_b32_e32 v73, 0xffff0000, v73
	v_lshlrev_b32_e32 v110, 16, v74
	v_and_b32_e32 v111, 0xffff0000, v74
	v_lshlrev_b32_e32 v74, 16, v75
	v_and_b32_e32 v75, 0xffff0000, v75
	v_pk_mul_f32 v[64:65], v[64:65], v[108:109]
	v_pk_mul_f32 v[66:67], v[66:67], v[72:73]
	v_pk_mul_f32 v[72:73], v[62:63], v[74:75]
	v_pk_mul_f32 v[62:63], v[60:61], v[110:111]
	v_cvt_pk_bf16_f32 v60, v64, v65
	v_lshl_add_u64 v[64:65], s[6:7], 0, v[100:101]
	v_cvt_pk_bf16_f32 v61, v66, v67
	v_cvt_pk_bf16_f32 v62, v62, v63
	v_cvt_pk_bf16_f32 v63, v72, v73
	v_lshl_add_u64 v[64:65], v[64:65], 0, v[2:3]
	global_store_dwordx4 v[64:65], v[60:63], off sc1
	v_lshlrev_b32_e32 v66, 16, v78
	v_and_b32_e32 v67, 0xffff0000, v78
	v_lshlrev_b32_e32 v60, 16, v76
	v_and_b32_e32 v61, 0xffff0000, v76
	v_lshlrev_b32_e32 v62, 16, v77
	v_and_b32_e32 v63, 0xffff0000, v77
	v_lshlrev_b32_e32 v72, 16, v79
	v_and_b32_e32 v73, 0xffff0000, v79
	v_pk_mul_f32 v[58:59], v[58:59], v[62:63]
	v_pk_mul_f32 v[56:57], v[56:57], v[60:61]
	v_pk_mul_f32 v[60:61], v[54:55], v[72:73]
	v_pk_mul_f32 v[54:55], v[52:53], v[66:67]
	v_cvt_pk_bf16_f32 v52, v56, v57
	v_cvt_pk_bf16_f32 v53, v58, v59
	v_cvt_pk_bf16_f32 v54, v54, v55
	v_cvt_pk_bf16_f32 v55, v60, v61
	global_store_dwordx4 v[64:65], v[52:55], off offset:256 sc1
	v_lshlrev_b32_e32 v56, 16, v81
	v_and_b32_e32 v57, 0xffff0000, v81
	v_lshlrev_b32_e32 v54, 16, v80
	v_and_b32_e32 v55, 0xffff0000, v80
	v_lshlrev_b64 v[52:53], 11, v[102:103]
	v_lshlrev_b32_e32 v58, 16, v82
	v_and_b32_e32 v59, 0xffff0000, v82
	v_lshlrev_b32_e32 v60, 16, v83
	v_and_b32_e32 v61, 0xffff0000, v83
	v_pk_mul_f32 v[48:49], v[48:49], v[54:55]
	v_pk_mul_f32 v[50:51], v[50:51], v[56:57]
	v_pk_mul_f32 v[54:55], v[46:47], v[60:61]
	v_pk_mul_f32 v[46:47], v[44:45], v[58:59]
	v_cvt_pk_bf16_f32 v44, v48, v49
	v_lshl_add_u64 v[48:49], s[6:7], 0, v[52:53]
	v_cvt_pk_bf16_f32 v45, v50, v51
	v_cvt_pk_bf16_f32 v46, v46, v47
	v_cvt_pk_bf16_f32 v47, v54, v55
	v_lshl_add_u64 v[48:49], v[48:49], 0, v[2:3]
	global_store_dwordx4 v[48:49], v[44:47], off sc1
	v_lshlrev_b32_e32 v50, 16, v86
	v_and_b32_e32 v51, 0xffff0000, v86
	v_lshlrev_b32_e32 v44, 16, v84
	v_and_b32_e32 v45, 0xffff0000, v84
	v_lshlrev_b32_e32 v46, 16, v85
	v_and_b32_e32 v47, 0xffff0000, v85
	v_lshlrev_b32_e32 v52, 16, v87
	v_and_b32_e32 v53, 0xffff0000, v87
	v_pk_mul_f32 v[42:43], v[42:43], v[46:47]
	v_pk_mul_f32 v[40:41], v[40:41], v[44:45]
	v_pk_mul_f32 v[44:45], v[38:39], v[52:53]
	v_pk_mul_f32 v[38:39], v[36:37], v[50:51]
	v_cvt_pk_bf16_f32 v36, v40, v41
	v_cvt_pk_bf16_f32 v37, v42, v43
	v_cvt_pk_bf16_f32 v38, v38, v39
	v_cvt_pk_bf16_f32 v39, v44, v45
	global_store_dwordx4 v[48:49], v[36:39], off offset:256 sc1
	v_lshlrev_b32_e32 v40, 16, v89
	v_and_b32_e32 v41, 0xffff0000, v89
	v_lshlrev_b32_e32 v38, 16, v88
	v_and_b32_e32 v39, 0xffff0000, v88
	v_lshlrev_b64 v[36:37], 11, v[104:105]
	v_lshlrev_b32_e32 v42, 16, v90
	v_and_b32_e32 v43, 0xffff0000, v90
	v_lshlrev_b32_e32 v44, 16, v91
	v_and_b32_e32 v45, 0xffff0000, v91
	v_pk_mul_f32 v[32:33], v[32:33], v[38:39]
	v_pk_mul_f32 v[34:35], v[34:35], v[40:41]
	v_pk_mul_f32 v[38:39], v[30:31], v[44:45]
	v_pk_mul_f32 v[30:31], v[28:29], v[42:43]
	v_cvt_pk_bf16_f32 v28, v32, v33
	v_lshl_add_u64 v[32:33], s[6:7], 0, v[36:37]
	v_cvt_pk_bf16_f32 v29, v34, v35
	v_cvt_pk_bf16_f32 v30, v30, v31
	v_cvt_pk_bf16_f32 v31, v38, v39
	v_lshl_add_u64 v[32:33], v[32:33], 0, v[2:3]
	global_store_dwordx4 v[32:33], v[28:31], off sc1
	v_lshlrev_b32_e32 v34, 16, v94
	v_and_b32_e32 v35, 0xffff0000, v94
	v_lshlrev_b32_e32 v28, 16, v92
	v_and_b32_e32 v29, 0xffff0000, v92
	v_lshlrev_b32_e32 v30, 16, v93
	v_and_b32_e32 v31, 0xffff0000, v93
	v_lshlrev_b32_e32 v36, 16, v95
	v_and_b32_e32 v37, 0xffff0000, v95
	v_pk_mul_f32 v[26:27], v[26:27], v[30:31]
	v_pk_mul_f32 v[24:25], v[24:25], v[28:29]
	v_pk_mul_f32 v[28:29], v[22:23], v[36:37]
	v_pk_mul_f32 v[22:23], v[20:21], v[34:35]
	v_cvt_pk_bf16_f32 v20, v24, v25
	v_cvt_pk_bf16_f32 v21, v26, v27
	v_cvt_pk_bf16_f32 v22, v22, v23
	v_cvt_pk_bf16_f32 v23, v28, v29
	global_store_dwordx4 v[32:33], v[20:23], off offset:256 sc1
	v_lshlrev_b32_e32 v24, 16, v97
	v_and_b32_e32 v25, 0xffff0000, v97
	v_lshlrev_b32_e32 v22, 16, v96
	v_and_b32_e32 v23, 0xffff0000, v96
	v_lshlrev_b64 v[20:21], 11, v[106:107]
	v_lshlrev_b32_e32 v26, 16, v98
	v_and_b32_e32 v27, 0xffff0000, v98
	v_lshlrev_b32_e32 v28, 16, v99
	v_and_b32_e32 v29, 0xffff0000, v99
	v_pk_mul_f32 v[16:17], v[16:17], v[22:23]
	v_pk_mul_f32 v[18:19], v[18:19], v[24:25]
	v_pk_mul_f32 v[22:23], v[14:15], v[28:29]
	v_pk_mul_f32 v[14:15], v[12:13], v[26:27]
	v_cvt_pk_bf16_f32 v12, v16, v17
	v_lshl_add_u64 v[16:17], s[6:7], 0, v[20:21]
	v_cvt_pk_bf16_f32 v13, v18, v19
	v_cvt_pk_bf16_f32 v14, v14, v15
	v_cvt_pk_bf16_f32 v15, v22, v23
	v_lshl_add_u64 v[16:17], v[16:17], 0, v[2:3]
	global_store_dwordx4 v[16:17], v[12:15], off sc1
	v_lshlrev_b32_e32 v2, 16, v68
	v_and_b32_e32 v3, 0xffff0000, v68
	v_lshlrev_b32_e32 v12, 16, v69
	v_and_b32_e32 v13, 0xffff0000, v69
	v_lshlrev_b32_e32 v14, 16, v70
	v_and_b32_e32 v15, 0xffff0000, v70
	v_lshlrev_b32_e32 v18, 16, v71
	v_and_b32_e32 v19, 0xffff0000, v71
	v_pk_mul_f32 v[10:11], v[10:11], v[12:13]
	v_pk_mul_f32 v[2:3], v[8:9], v[2:3]
	v_pk_mul_f32 v[6:7], v[6:7], v[18:19]
	v_pk_mul_f32 v[4:5], v[4:5], v[14:15]
	v_cvt_pk_bf16_f32 v2, v2, v3
	v_cvt_pk_bf16_f32 v3, v10, v11
	v_cvt_pk_bf16_f32 v4, v4, v5
	v_cvt_pk_bf16_f32 v5, v6, v7
	global_store_dwordx4 v[16:17], v[2:5], off offset:256 sc1
	s_cbranch_vccnz .LBB0_118
	v_readlane_b32 s0, v252, 41
	v_readlane_b32 s1, v252, 42
	s_andn2_b64 vcc, exec, s[0:1]
	s_cbranch_vccnz .LBB0_117
	s_barrier
	s_branch .LBB0_117

.LBB0_271:
	s_lshl_b32 s0, s3, 8
	v_readlane_b32 s12, v252, 26
	v_add_u32_e32 v174, s0, v155
	s_add_i32 s0, s0, s12
	s_cmp_lt_i32 s0, 0x8000
	s_movk_i32 s1, 0xf800
	s_cselect_b32 s1, s1, 0x7fffe000
	s_cselect_b32 s20, 11, 13
	s_and_b32 s0, s1, s0
	s_sub_i32 s3, s0, s12
	s_add_i32 s21, s83, -5
	s_add_i32 s4, s83, -10
	s_cmp_lt_i32 s83, 10
	s_cselect_b32 s0, s21, s4
	s_cmp_eq_u32 s0, 2
	s_cselect_b32 s1, 4, 0
	s_cmp_lg_u32 s0, 1
	s_cselect_b32 s82, s1, 2
	s_cmp_gt_i32 s83, 9
	s_mov_b64 s[0:1], -1
	v_readlane_b32 s13, v252, 27
	s_cbranch_scc0 .LBB0_278
	s_cmp_gt_u32 s83, 14
	s_cbranch_scc0 .LBB0_274
	v_lshl_add_u32 v176, s83, 7, v190
	v_mov_b32_e32 v177, v0
	v_readlane_b32 s0, v252, 29
	v_lshlrev_b64 v[130:131], 2, v[176:177]
	v_readlane_b32 s1, v252, 30
	v_ashrrev_i32_e32 v175, 31, v174
	v_lshlrev_b64 v[178:179], 12, v[174:175]
	v_lshl_add_u64 v[132:133], s[0:1], 0, v[130:131]
	v_readlane_b32 s0, v252, 38
	v_readlane_b32 s1, v252, 39
	v_lshl_add_u64 v[188:189], s[10:11], 0, v[178:179]
	s_nop 0
	v_lshl_add_u64 v[138:139], s[0:1], 0, v[130:131]
	global_load_dwordx4 v[134:137], v[132:133], off offset:16
	global_load_dwordx4 v[142:145], v[132:133], off
	s_nop 0
	global_load_dwordx4 v[130:133], v[138:139], off offset:16
	s_nop 0
	global_load_dwordx4 v[138:141], v[138:139], off
	s_mov_b64 s[0:1], 0x80000
	s_waitcnt vmcnt(0)
	v_add_f32_e32 v175, v126, v142
	v_mul_f32_e32 v175, 0xbfb8aa3b, v175
	v_exp_f32_e32 v178, v175
	v_add_f32_e32 v175, v118, v138
	v_mul_f32_e32 v175, 0xbfb8aa3b, v175
	v_exp_f32_e32 v175, v175
	v_add_f32_e32 v183, v121, v141
	v_mul_f32_e32 v183, 0xbfb8aa3b, v183
	v_exp_f32_e32 v183, v183
	v_add_f32_e32 v175, 1.0, v175
	v_rcp_f32_e32 v180, v175
	v_add_f32_e32 v175, v127, v143
	v_mul_f32_e32 v175, 0xbfb8aa3b, v175
	v_exp_f32_e32 v179, v175
	v_add_f32_e32 v175, v119, v139
	v_mul_f32_e32 v175, 0xbfb8aa3b, v175
	v_exp_f32_e32 v175, v175
	v_pk_add_f32 v[178:179], v[178:179], 1.0 op_sel_hi:[1,0]
	v_add_f32_e32 v183, 1.0, v183
	v_rcp_f32_e32 v193, v179
	v_add_f32_e32 v175, 1.0, v175
	v_rcp_f32_e32 v181, v175
	v_rcp_f32_e32 v175, v178
	v_rcp_f32_e32 v183, v183
	v_add_f32_e32 v185, v115, v131
	v_pk_mul_f32 v[180:181], v[178:179], v[180:181]
	v_add_f32_e32 v179, v120, v140
	v_mul_f32_e32 v179, 0xbfb8aa3b, v179
	v_exp_f32_e32 v179, v179
	v_add_f32_e32 v178, v128, v144
	v_mul_f32_e32 v178, 0xbfb8aa3b, v178
	v_exp_f32_e32 v178, v178
	v_add_f32_e32 v179, 1.0, v179
	v_rcp_f32_e32 v182, v179
	v_add_f32_e32 v179, v129, v145
	v_mul_f32_e32 v179, 0xbfb8aa3b, v179
	v_exp_f32_e32 v179, v179
	v_mul_f32_e32 v185, 0xbfb8aa3b, v185
	v_exp_f32_e32 v185, v185
	v_add_f32_e32 v187, v117, v133
	v_pk_add_f32 v[178:179], v[178:179], 1.0 op_sel_hi:[1,0]
	v_mul_f32_e32 v187, 0xbfb8aa3b, v187
	v_rcp_f32_e32 v195, v179
	v_pk_mul_f32 v[182:183], v[178:179], v[182:183]
	v_add_f32_e32 v179, v114, v130
	v_mul_f32_e32 v179, 0xbfb8aa3b, v179
	v_exp_f32_e32 v179, v179
	v_rcp_f32_e32 v194, v178
	v_add_f32_e32 v178, v122, v134
	v_mul_f32_e32 v178, 0xbfb8aa3b, v178
	v_add_f32_e32 v179, 1.0, v179
	v_rcp_f32_e32 v184, v179
	v_add_f32_e32 v179, v123, v135
	v_mul_f32_e32 v179, 0xbfb8aa3b, v179
	v_exp_f32_e32 v178, v178
	v_exp_f32_e32 v179, v179
	v_add_f32_e32 v185, 1.0, v185
	v_rcp_f32_e32 v185, v185
	v_exp_f32_e32 v187, v187
	v_pk_add_f32 v[178:179], v[178:179], 1.0 op_sel_hi:[1,0]
	v_cvt_pk_bf16_f32 v208, v175, v193
	v_rcp_f32_e32 v197, v179
	v_pk_mul_f32 v[184:185], v[178:179], v[184:185]
	v_add_f32_e32 v179, v116, v132
	v_mul_f32_e32 v179, 0xbfb8aa3b, v179
	v_exp_f32_e32 v179, v179
	v_rcp_f32_e32 v196, v178
	v_add_f32_e32 v178, v124, v136
	v_mul_f32_e32 v178, 0xbfb8aa3b, v178
	v_add_f32_e32 v179, 1.0, v179
	v_rcp_f32_e32 v186, v179
	v_add_f32_e32 v179, v125, v137
	v_mul_f32_e32 v179, 0xbfb8aa3b, v179
	v_exp_f32_e32 v178, v178
	v_exp_f32_e32 v179, v179
	v_add_f32_e32 v187, 1.0, v187
	v_rcp_f32_e32 v187, v187
	v_add_f32_e32 v175, v110, v142
	v_pk_add_f32 v[178:179], v[178:179], 1.0 op_sel_hi:[1,0]
	v_cvt_pk_bf16_f32 v180, v180, v181
	v_rcp_f32_e32 v198, v178
	v_pk_mul_f32 v[186:187], v[178:179], v[186:187]
	v_rcp_f32_e32 v199, v179
	v_lshlrev_b64 v[178:179], 1, v[176:177]
	v_lshl_add_u64 v[176:177], v[188:189], 0, v[178:179]
	v_cvt_pk_bf16_f32 v181, v182, v183
	v_cvt_pk_bf16_f32 v182, v184, v185
	v_cvt_pk_bf16_f32 v183, v186, v187
	v_mul_f32_e32 v175, 0xbfb8aa3b, v175
	global_store_dwordx4 v[176:177], v[180:183], off offset:2048 sc1 nt
	v_add_f32_e32 v187, v105, v141
	v_mul_f32_e32 v187, 0xbfb8aa3b, v187
	v_exp_f32_e32 v182, v175
	v_add_f32_e32 v175, v102, v138
	v_mul_f32_e32 v175, 0xbfb8aa3b, v175
	v_exp_f32_e32 v175, v175
	v_exp_f32_e32 v187, v187
	v_cvt_pk_bf16_f32 v211, v198, v199
	v_add_f32_e32 v189, v99, v131
	v_add_f32_e32 v175, 1.0, v175
	v_rcp_f32_e32 v184, v175
	v_add_f32_e32 v175, v111, v143
	v_mul_f32_e32 v175, 0xbfb8aa3b, v175
	v_exp_f32_e32 v183, v175
	v_add_f32_e32 v175, v103, v139
	v_mul_f32_e32 v175, 0xbfb8aa3b, v175
	v_exp_f32_e32 v175, v175
	v_pk_add_f32 v[182:183], v[182:183], 1.0 op_sel_hi:[1,0]
	v_add_f32_e32 v187, 1.0, v187
	v_rcp_f32_e32 v193, v183
	v_add_f32_e32 v175, 1.0, v175
	v_rcp_f32_e32 v185, v175
	v_rcp_f32_e32 v175, v182
	v_rcp_f32_e32 v187, v187
	v_mul_f32_e32 v189, 0xbfb8aa3b, v189
	v_pk_mul_f32 v[184:185], v[182:183], v[184:185]
	v_add_f32_e32 v183, v104, v140
	v_mul_f32_e32 v183, 0xbfb8aa3b, v183
	v_exp_f32_e32 v183, v183
	v_add_f32_e32 v182, v112, v144
	v_mul_f32_e32 v182, 0xbfb8aa3b, v182
	v_exp_f32_e32 v182, v182
	v_add_f32_e32 v183, 1.0, v183
	v_rcp_f32_e32 v186, v183
	v_add_f32_e32 v183, v113, v145
	v_mul_f32_e32 v183, 0xbfb8aa3b, v183
	v_exp_f32_e32 v183, v183
	v_exp_f32_e32 v189, v189
	v_cvt_pk_bf16_f32 v209, v194, v195
	v_cvt_pk_bf16_f32 v210, v196, v197
	v_pk_add_f32 v[182:183], v[182:183], 1.0 op_sel_hi:[1,0]
	v_add_f32_e32 v189, 1.0, v189
	v_pk_mul_f32 v[186:187], v[182:183], v[186:187]
	v_rcp_f32_e32 v199, v183
	v_add_f32_e32 v183, v98, v130
	v_mul_f32_e32 v183, 0xbfb8aa3b, v183
	v_exp_f32_e32 v183, v183
	v_rcp_f32_e32 v198, v182
	v_add_f32_e32 v182, v106, v134
	v_mul_f32_e32 v182, 0xbfb8aa3b, v182
	v_add_f32_e32 v183, 1.0, v183
	v_rcp_f32_e32 v188, v183
	v_add_f32_e32 v183, v107, v135
	v_mul_f32_e32 v183, 0xbfb8aa3b, v183
	v_exp_f32_e32 v182, v182
	v_exp_f32_e32 v183, v183
	v_rcp_f32_e32 v189, v189
	global_store_dwordx4 v[176:177], v[208:211], off sc1 nt
	v_add_f32_e32 v195, v101, v133
	v_pk_add_f32 v[182:183], v[182:183], 1.0 op_sel_hi:[1,0]
	v_mul_f32_e32 v195, 0xbfb8aa3b, v195
	v_pk_mul_f32 v[188:189], v[182:183], v[188:189]
	v_rcp_f32_e32 v209, v183
	v_add_f32_e32 v183, v100, v132
	v_mul_f32_e32 v183, 0xbfb8aa3b, v183
	v_exp_f32_e32 v183, v183
	v_exp_f32_e32 v195, v195
	v_rcp_f32_e32 v208, v182
	v_add_f32_e32 v182, v108, v136
	v_add_f32_e32 v183, 1.0, v183
	v_rcp_f32_e32 v194, v183
	v_add_f32_e32 v183, v109, v137
	v_mul_f32_e32 v182, 0xbfb8aa3b, v182
	v_mul_f32_e32 v183, 0xbfb8aa3b, v183
	v_exp_f32_e32 v182, v182
	v_exp_f32_e32 v183, v183
	v_add_f32_e32 v195, 1.0, v195
	v_rcp_f32_e32 v195, v195
	v_or_b32_e32 v180, 16, v174
	v_pk_add_f32 v[182:183], v[182:183], 1.0 op_sel_hi:[1,0]
	v_ashrrev_i32_e32 v181, 31, v180
	v_rcp_f32_e32 v210, v182
	v_pk_mul_f32 v[194:195], v[182:183], v[194:195]
	v_rcp_f32_e32 v183, v183
	v_lshlrev_b64 v[180:181], 12, v[180:181]
	v_lshl_add_u64 v[180:181], s[10:11], 0, v[180:181]
	v_lshl_add_u64 v[196:197], v[180:181], 0, v[178:179]
	v_cvt_pk_bf16_f32 v180, v175, v193
	v_cvt_pk_bf16_f32 v181, v198, v199
	v_cvt_pk_bf16_f32 v182, v208, v209
	v_cvt_pk_bf16_f32 v183, v210, v183
	v_add_f32_e32 v175, v94, v142
	global_store_dwordx4 v[196:197], v[180:183], off sc1 nt
	v_mul_f32_e32 v175, 0xbfb8aa3b, v175
	s_nop 0
	v_cvt_pk_bf16_f32 v180, v184, v185
	v_cvt_pk_bf16_f32 v181, v186, v187
	v_cvt_pk_bf16_f32 v182, v188, v189
	v_cvt_pk_bf16_f32 v183, v194, v195
	global_store_dwordx4 v[196:197], v[180:183], off offset:2048 sc1 nt
	v_add_f32_e32 v187, v89, v141
	v_mul_f32_e32 v187, 0xbfb8aa3b, v187
	v_exp_f32_e32 v182, v175
	v_add_f32_e32 v175, v86, v138
	v_mul_f32_e32 v175, 0xbfb8aa3b, v175
	v_exp_f32_e32 v175, v175
	v_exp_f32_e32 v187, v187
	v_add_f32_e32 v189, v83, v131
	v_mul_f32_e32 v189, 0xbfb8aa3b, v189
	v_add_f32_e32 v175, 1.0, v175
	v_rcp_f32_e32 v184, v175
	v_add_f32_e32 v175, v95, v143
	v_mul_f32_e32 v175, 0xbfb8aa3b, v175
	v_exp_f32_e32 v183, v175
	v_add_f32_e32 v175, v87, v139
	v_mul_f32_e32 v175, 0xbfb8aa3b, v175
	v_exp_f32_e32 v175, v175
	v_pk_add_f32 v[182:183], v[182:183], 1.0 op_sel_hi:[1,0]
	v_add_f32_e32 v187, 1.0, v187
	v_rcp_f32_e32 v193, v183
	v_add_f32_e32 v175, 1.0, v175
	v_rcp_f32_e32 v185, v175
	v_rcp_f32_e32 v175, v182
	v_rcp_f32_e32 v187, v187
	v_exp_f32_e32 v189, v189
	v_pk_mul_f32 v[184:185], v[182:183], v[184:185]
	v_add_f32_e32 v183, v88, v140
	v_mul_f32_e32 v183, 0xbfb8aa3b, v183
	v_exp_f32_e32 v183, v183
	v_add_f32_e32 v182, v96, v144
	v_mul_f32_e32 v182, 0xbfb8aa3b, v182
	v_exp_f32_e32 v182, v182
	v_add_f32_e32 v183, 1.0, v183
	v_rcp_f32_e32 v186, v183
	v_add_f32_e32 v183, v97, v145
	v_mul_f32_e32 v183, 0xbfb8aa3b, v183
	v_exp_f32_e32 v183, v183
	v_add_f32_e32 v189, 1.0, v189
	v_rcp_f32_e32 v189, v189
	v_add_f32_e32 v195, v85, v133
	v_pk_add_f32 v[182:183], v[182:183], 1.0 op_sel_hi:[1,0]
	v_mul_f32_e32 v195, 0xbfb8aa3b, v195
	v_pk_mul_f32 v[186:187], v[182:183], v[186:187]
	v_rcp_f32_e32 v199, v183
	v_add_f32_e32 v183, v82, v130
	v_mul_f32_e32 v183, 0xbfb8aa3b, v183
	v_exp_f32_e32 v183, v183
	v_rcp_f32_e32 v198, v182
	v_add_f32_e32 v182, v90, v134
	v_mul_f32_e32 v182, 0xbfb8aa3b, v182
	v_add_f32_e32 v183, 1.0, v183
	v_rcp_f32_e32 v188, v183
	v_add_f32_e32 v183, v91, v135
	v_mul_f32_e32 v183, 0xbfb8aa3b, v183
	v_exp_f32_e32 v182, v182
	v_exp_f32_e32 v183, v183
	v_exp_f32_e32 v195, v195
	v_or_b32_e32 v180, 32, v174
	v_ashrrev_i32_e32 v181, 31, v180
	v_pk_add_f32 v[182:183], v[182:183], 1.0 op_sel_hi:[1,0]
	v_add_f32_e32 v195, 1.0, v195
	v_pk_mul_f32 v[188:189], v[182:183], v[188:189]
	v_rcp_f32_e32 v209, v183
	v_add_f32_e32 v183, v84, v132
	v_mul_f32_e32 v183, 0xbfb8aa3b, v183
	v_exp_f32_e32 v183, v183
	v_rcp_f32_e32 v208, v182
	v_add_f32_e32 v182, v92, v136
	v_mul_f32_e32 v182, 0xbfb8aa3b, v182
	v_add_f32_e32 v183, 1.0, v183
	v_rcp_f32_e32 v194, v183
	v_add_f32_e32 v183, v93, v137
	v_mul_f32_e32 v183, 0xbfb8aa3b, v183
	v_exp_f32_e32 v182, v182
	v_exp_f32_e32 v183, v183
	v_rcp_f32_e32 v195, v195
	v_lshlrev_b64 v[180:181], 12, v[180:181]
	v_lshl_add_u64 v[180:181], s[10:11], 0, v[180:181]
	v_pk_add_f32 v[182:183], v[182:183], 1.0 op_sel_hi:[1,0]
	v_lshl_add_u64 v[196:197], v[180:181], 0, v[178:179]
	v_rcp_f32_e32 v210, v182
	v_pk_mul_f32 v[194:195], v[182:183], v[194:195]
	v_rcp_f32_e32 v183, v183
	v_cvt_pk_bf16_f32 v180, v175, v193
	v_cvt_pk_bf16_f32 v181, v198, v199
	v_cvt_pk_bf16_f32 v182, v208, v209
	v_cvt_pk_bf16_f32 v183, v210, v183
	v_add_f32_e32 v175, v78, v142
	global_store_dwordx4 v[196:197], v[180:183], off sc1 nt
	v_mul_f32_e32 v175, 0xbfb8aa3b, v175
	s_nop 0
	v_cvt_pk_bf16_f32 v180, v184, v185
	v_cvt_pk_bf16_f32 v181, v186, v187
	v_cvt_pk_bf16_f32 v182, v188, v189
	v_cvt_pk_bf16_f32 v183, v194, v195
	global_store_dwordx4 v[196:197], v[180:183], off offset:2048 sc1 nt
	v_add_f32_e32 v187, v73, v141
	v_mul_f32_e32 v187, 0xbfb8aa3b, v187
	v_exp_f32_e32 v182, v175
	v_add_f32_e32 v175, v70, v138
	v_mul_f32_e32 v175, 0xbfb8aa3b, v175
	v_exp_f32_e32 v175, v175
	v_exp_f32_e32 v187, v187
	v_add_f32_e32 v189, v67, v131
	v_mul_f32_e32 v189, 0xbfb8aa3b, v189
	v_add_f32_e32 v175, 1.0, v175
	v_rcp_f32_e32 v184, v175
	v_add_f32_e32 v175, v79, v143
	v_mul_f32_e32 v175, 0xbfb8aa3b, v175
	v_exp_f32_e32 v183, v175
	v_add_f32_e32 v175, v71, v139
	v_mul_f32_e32 v175, 0xbfb8aa3b, v175
	v_exp_f32_e32 v175, v175
	v_pk_add_f32 v[182:183], v[182:183], 1.0 op_sel_hi:[1,0]
	v_add_f32_e32 v187, 1.0, v187
	v_rcp_f32_e32 v193, v183
	v_add_f32_e32 v175, 1.0, v175
	v_rcp_f32_e32 v185, v175
	v_rcp_f32_e32 v175, v182
	v_rcp_f32_e32 v187, v187
	v_exp_f32_e32 v189, v189
	v_pk_mul_f32 v[184:185], v[182:183], v[184:185]
	v_add_f32_e32 v183, v72, v140
	v_mul_f32_e32 v183, 0xbfb8aa3b, v183
	v_exp_f32_e32 v183, v183
	v_add_f32_e32 v182, v80, v144
	v_mul_f32_e32 v182, 0xbfb8aa3b, v182
	v_exp_f32_e32 v182, v182
	v_add_f32_e32 v183, 1.0, v183
	v_rcp_f32_e32 v186, v183
	v_add_f32_e32 v183, v81, v145
	v_mul_f32_e32 v183, 0xbfb8aa3b, v183
	v_exp_f32_e32 v183, v183
	v_add_f32_e32 v189, 1.0, v189
	v_rcp_f32_e32 v189, v189
	v_add_f32_e32 v195, v69, v133
	v_pk_add_f32 v[182:183], v[182:183], 1.0 op_sel_hi:[1,0]
	v_mul_f32_e32 v195, 0xbfb8aa3b, v195
	v_pk_mul_f32 v[186:187], v[182:183], v[186:187]
	v_rcp_f32_e32 v197, v183
	v_add_f32_e32 v183, v66, v130
	v_mul_f32_e32 v183, 0xbfb8aa3b, v183
	v_exp_f32_e32 v183, v183
	v_rcp_f32_e32 v196, v182
	v_add_f32_e32 v182, v74, v134
	v_mul_f32_e32 v182, 0xbfb8aa3b, v182
	v_add_f32_e32 v183, 1.0, v183
	v_rcp_f32_e32 v188, v183
	v_add_f32_e32 v183, v75, v135
	v_mul_f32_e32 v183, 0xbfb8aa3b, v183
	v_exp_f32_e32 v182, v182
	v_exp_f32_e32 v183, v183
	v_exp_f32_e32 v195, v195
	v_or_b32_e32 v180, 48, v174
	v_ashrrev_i32_e32 v181, 31, v180
	v_pk_add_f32 v[182:183], v[182:183], 1.0 op_sel_hi:[1,0]
	v_add_f32_e32 v195, 1.0, v195
	v_pk_mul_f32 v[188:189], v[182:183], v[188:189]
	v_rcp_f32_e32 v199, v183
	v_add_f32_e32 v183, v68, v132
	v_mul_f32_e32 v183, 0xbfb8aa3b, v183
	v_exp_f32_e32 v183, v183
	v_rcp_f32_e32 v198, v182
	v_add_f32_e32 v182, v76, v136
	v_mul_f32_e32 v182, 0xbfb8aa3b, v182
	v_add_f32_e32 v183, 1.0, v183
	v_rcp_f32_e32 v194, v183
	v_add_f32_e32 v183, v77, v137
	v_mul_f32_e32 v183, 0xbfb8aa3b, v183
	v_exp_f32_e32 v182, v182
	v_exp_f32_e32 v183, v183
	v_rcp_f32_e32 v195, v195
	v_lshlrev_b64 v[180:181], 12, v[180:181]
	v_lshl_add_u64 v[180:181], s[10:11], 0, v[180:181]
	v_pk_add_f32 v[182:183], v[182:183], 1.0 op_sel_hi:[1,0]
	s_nop 0
	v_rcp_f32_e32 v208, v182
	v_rcp_f32_e32 v209, v183
	v_pk_mul_f32 v[194:195], v[182:183], v[194:195]
	v_lshl_add_u64 v[182:183], v[180:181], 0, v[178:179]
	v_cvt_pk_bf16_f32 v178, v175, v193
	v_cvt_pk_bf16_f32 v179, v196, v197
	v_cvt_pk_bf16_f32 v180, v198, v199
	v_cvt_pk_bf16_f32 v181, v208, v209
	v_add_f32_e32 v175, v62, v142
	global_store_dwordx4 v[182:183], v[178:181], off sc1 nt
	v_mul_f32_e32 v175, 0xbfb8aa3b, v175
	s_nop 0
	v_cvt_pk_bf16_f32 v178, v184, v185
	v_cvt_pk_bf16_f32 v179, v186, v187
	v_cvt_pk_bf16_f32 v180, v188, v189
	v_cvt_pk_bf16_f32 v181, v194, v195
	global_store_dwordx4 v[182:183], v[178:181], off offset:2048 sc1 nt
	v_lshl_add_u64 v[194:195], v[176:177], 0, s[0:1]
	s_mov_b32 s0, 0x80000
	v_exp_f32_e32 v178, v175
	v_add_f32_e32 v175, v54, v138
	v_mul_f32_e32 v175, 0xbfb8aa3b, v175
	v_exp_f32_e32 v175, v175
	s_nop 0
	v_add_f32_e32 v175, 1.0, v175
	v_rcp_f32_e32 v180, v175
	v_add_f32_e32 v175, v63, v143
	v_mul_f32_e32 v175, 0xbfb8aa3b, v175
	v_exp_f32_e32 v179, v175
	v_add_f32_e32 v175, v55, v139
	v_mul_f32_e32 v175, 0xbfb8aa3b, v175
	v_exp_f32_e32 v175, v175
	v_pk_add_f32 v[182:183], v[178:179], 1.0 op_sel_hi:[1,0]
	v_add_f32_e32 v175, 1.0, v175
	v_rcp_f32_e32 v181, v175
	v_rcp_f32_e32 v193, v183
	v_rcp_f32_e32 v175, v182
	v_pk_mul_f32 v[178:179], v[182:183], v[180:181]
	v_add_f32_e32 v181, v56, v140
	v_mul_f32_e32 v181, 0xbfb8aa3b, v181
	v_exp_f32_e32 v181, v181
	v_add_f32_e32 v183, v57, v141
	v_mul_f32_e32 v183, 0xbfb8aa3b, v183
	v_exp_f32_e32 v183, v183
	v_add_f32_e32 v181, 1.0, v181
	v_add_f32_e32 v180, v64, v144
	v_rcp_f32_e32 v182, v181
	v_add_f32_e32 v181, v65, v145
	v_mul_f32_e32 v180, 0xbfb8aa3b, v180
	v_mul_f32_e32 v181, 0xbfb8aa3b, v181
	v_exp_f32_e32 v180, v180
	v_exp_f32_e32 v181, v181
	v_add_f32_e32 v183, 1.0, v183
	v_rcp_f32_e32 v183, v183
	v_cvt_pk_bf16_f32 v178, v178, v179
	v_pk_add_f32 v[180:181], v[180:181], 1.0 op_sel_hi:[1,0]
	s_nop 0
	v_pk_mul_f32 v[184:185], v[180:181], v[182:183]
	v_rcp_f32_e32 v197, v181
	v_add_f32_e32 v181, v50, v130
	v_mul_f32_e32 v181, 0xbfb8aa3b, v181
	v_exp_f32_e32 v181, v181
	v_add_f32_e32 v183, v51, v131
	v_mul_f32_e32 v183, 0xbfb8aa3b, v183
	v_exp_f32_e32 v183, v183
	v_add_f32_e32 v181, 1.0, v181
	v_rcp_f32_e32 v196, v180
	v_add_f32_e32 v180, v58, v134
	v_rcp_f32_e32 v182, v181
	v_add_f32_e32 v181, v59, v135
	v_mul_f32_e32 v180, 0xbfb8aa3b, v180
	v_mul_f32_e32 v181, 0xbfb8aa3b, v181
	v_exp_f32_e32 v180, v180
	v_exp_f32_e32 v181, v181
	v_add_f32_e32 v183, 1.0, v183
	v_rcp_f32_e32 v183, v183
	v_cvt_pk_bf16_f32 v179, v184, v185
	v_pk_add_f32 v[180:181], v[180:181], 1.0 op_sel_hi:[1,0]
	s_nop 0
	v_pk_mul_f32 v[186:187], v[180:181], v[182:183]
	v_rcp_f32_e32 v199, v181
	v_add_f32_e32 v181, v52, v132
	v_mul_f32_e32 v181, 0xbfb8aa3b, v181
	v_exp_f32_e32 v181, v181
	v_add_f32_e32 v183, v53, v133
	v_mul_f32_e32 v183, 0xbfb8aa3b, v183
	v_exp_f32_e32 v183, v183
	v_add_f32_e32 v181, 1.0, v181
	v_rcp_f32_e32 v198, v180
	v_add_f32_e32 v180, v60, v136
	v_rcp_f32_e32 v182, v181
	v_add_f32_e32 v181, v61, v137
	v_mul_f32_e32 v180, 0xbfb8aa3b, v180
	v_mul_f32_e32 v181, 0xbfb8aa3b, v181
	v_exp_f32_e32 v180, v180
	v_exp_f32_e32 v181, v181
	v_add_f32_e32 v183, 1.0, v183
	v_rcp_f32_e32 v183, v183
	v_pk_add_f32 v[180:181], v[180:181], 1.0 op_sel_hi:[1,0]
	s_nop 0
	v_rcp_f32_e32 v208, v180
	v_pk_mul_f32 v[188:189], v[180:181], v[182:183]
	v_rcp_f32_e32 v183, v181
	v_cvt_pk_bf16_f32 v181, v196, v197
	v_add_co_u32_e32 v196, vcc, s0, v176
	v_cvt_pk_bf16_f32 v180, v175, v193
	v_cvt_pk_bf16_f32 v182, v198, v199
	v_cvt_pk_bf16_f32 v183, v208, v183
	v_addc_co_u32_e32 v197, vcc, 0, v177, vcc
	v_add_f32_e32 v175, v46, v142
	global_store_dwordx4 v[196:197], v[180:183], off sc1 nt
	v_mul_f32_e32 v175, 0xbfb8aa3b, v175
	s_mov_b64 s[0:1], 0x90000
	v_cvt_pk_bf16_f32 v180, v186, v187
	v_cvt_pk_bf16_f32 v181, v188, v189
	global_store_dwordx4 v[194:195], v[178:181], off offset:2048 sc1 nt
	v_lshl_add_u64 v[194:195], v[176:177], 0, s[0:1]
	s_mov_b64 s[0:1], 0xa0000
	v_exp_f32_e32 v178, v175
	v_add_f32_e32 v175, v38, v138
	v_mul_f32_e32 v175, 0xbfb8aa3b, v175
	v_exp_f32_e32 v175, v175
	s_nop 0
	v_add_f32_e32 v175, 1.0, v175
	v_rcp_f32_e32 v180, v175
	v_add_f32_e32 v175, v47, v143
	v_mul_f32_e32 v175, 0xbfb8aa3b, v175
	v_exp_f32_e32 v179, v175
	v_add_f32_e32 v175, v39, v139
	v_mul_f32_e32 v175, 0xbfb8aa3b, v175
	v_exp_f32_e32 v175, v175
	v_pk_add_f32 v[182:183], v[178:179], 1.0 op_sel_hi:[1,0]
	v_add_f32_e32 v175, 1.0, v175
	v_rcp_f32_e32 v181, v175
	v_rcp_f32_e32 v193, v183
	v_rcp_f32_e32 v175, v182
	v_pk_mul_f32 v[178:179], v[182:183], v[180:181]
	v_add_f32_e32 v181, v40, v140
	v_mul_f32_e32 v181, 0xbfb8aa3b, v181
	v_exp_f32_e32 v181, v181
	v_add_f32_e32 v183, v41, v141
	v_mul_f32_e32 v183, 0xbfb8aa3b, v183
	v_exp_f32_e32 v183, v183
	v_add_f32_e32 v181, 1.0, v181
	v_add_f32_e32 v180, v48, v144
	v_rcp_f32_e32 v182, v181
	v_add_f32_e32 v181, v49, v145
	v_mul_f32_e32 v180, 0xbfb8aa3b, v180
	v_mul_f32_e32 v181, 0xbfb8aa3b, v181
	v_exp_f32_e32 v180, v180
	v_exp_f32_e32 v181, v181
	v_add_f32_e32 v183, 1.0, v183
	v_rcp_f32_e32 v183, v183
	v_cvt_pk_bf16_f32 v178, v178, v179
	v_pk_add_f32 v[180:181], v[180:181], 1.0 op_sel_hi:[1,0]
	s_nop 0
	v_pk_mul_f32 v[184:185], v[180:181], v[182:183]
	v_rcp_f32_e32 v197, v181
	v_add_f32_e32 v181, v34, v130
	v_mul_f32_e32 v181, 0xbfb8aa3b, v181
	v_exp_f32_e32 v181, v181
	v_add_f32_e32 v183, v35, v131
	v_mul_f32_e32 v183, 0xbfb8aa3b, v183
	v_exp_f32_e32 v183, v183
	v_add_f32_e32 v181, 1.0, v181
	v_rcp_f32_e32 v196, v180
	v_add_f32_e32 v180, v42, v134
	v_rcp_f32_e32 v182, v181
	v_add_f32_e32 v181, v43, v135
	v_mul_f32_e32 v180, 0xbfb8aa3b, v180
	v_mul_f32_e32 v181, 0xbfb8aa3b, v181
	v_exp_f32_e32 v180, v180
	v_exp_f32_e32 v181, v181
	v_add_f32_e32 v183, 1.0, v183
	v_rcp_f32_e32 v183, v183
	v_cvt_pk_bf16_f32 v179, v184, v185
	v_pk_add_f32 v[180:181], v[180:181], 1.0 op_sel_hi:[1,0]
	s_nop 0
	v_pk_mul_f32 v[186:187], v[180:181], v[182:183]
	v_rcp_f32_e32 v199, v181
	v_add_f32_e32 v181, v36, v132
	v_mul_f32_e32 v181, 0xbfb8aa3b, v181
	v_exp_f32_e32 v181, v181
	v_add_f32_e32 v183, v37, v133
	v_mul_f32_e32 v183, 0xbfb8aa3b, v183
	v_exp_f32_e32 v183, v183
	v_add_f32_e32 v181, 1.0, v181
	v_rcp_f32_e32 v198, v180
	v_add_f32_e32 v180, v44, v136
	v_rcp_f32_e32 v182, v181
	v_add_f32_e32 v181, v45, v137
	v_mul_f32_e32 v180, 0xbfb8aa3b, v180
	v_mul_f32_e32 v181, 0xbfb8aa3b, v181
	v_exp_f32_e32 v180, v180
	v_exp_f32_e32 v181, v181
	v_add_f32_e32 v183, 1.0, v183
	v_rcp_f32_e32 v183, v183
	v_pk_add_f32 v[180:181], v[180:181], 1.0 op_sel_hi:[1,0]
	s_nop 0
	v_rcp_f32_e32 v208, v180
	v_pk_mul_f32 v[188:189], v[180:181], v[182:183]
	v_rcp_f32_e32 v183, v181
	v_cvt_pk_bf16_f32 v181, v196, v197
	v_add_co_u32_e32 v196, vcc, s86, v176
	v_cvt_pk_bf16_f32 v180, v175, v193
	v_cvt_pk_bf16_f32 v182, v198, v199
	v_cvt_pk_bf16_f32 v183, v208, v183
	v_addc_co_u32_e32 v197, vcc, 0, v177, vcc
	v_add_f32_e32 v175, v30, v142
	global_store_dwordx4 v[196:197], v[180:183], off sc1 nt
	v_mul_f32_e32 v175, 0xbfb8aa3b, v175
	v_add_f32_e32 v142, v14, v142
	v_cvt_pk_bf16_f32 v180, v186, v187
	v_cvt_pk_bf16_f32 v181, v188, v189
	global_store_dwordx4 v[194:195], v[178:181], off offset:2048 sc1 nt
	v_mul_f32_e32 v142, 0xbfb8aa3b, v142
	v_exp_f32_e32 v142, v142
	v_exp_f32_e32 v178, v175
	v_add_f32_e32 v175, v22, v138
	v_mul_f32_e32 v175, 0xbfb8aa3b, v175
	v_exp_f32_e32 v175, v175
	v_add_f32_e32 v138, v6, v138
	v_mul_f32_e32 v138, 0xbfb8aa3b, v138
	v_exp_f32_e32 v138, v138
	v_add_f32_e32 v175, 1.0, v175
	v_rcp_f32_e32 v180, v175
	v_add_f32_e32 v175, v31, v143
	v_mul_f32_e32 v175, 0xbfb8aa3b, v175
	v_exp_f32_e32 v179, v175
	v_add_f32_e32 v175, v23, v139
	v_mul_f32_e32 v175, 0xbfb8aa3b, v175
	v_exp_f32_e32 v175, v175
	v_pk_add_f32 v[182:183], v[178:179], 1.0 op_sel_hi:[1,0]
	v_add_f32_e32 v139, v7, v139
	v_rcp_f32_e32 v193, v183
	v_add_f32_e32 v175, 1.0, v175
	v_rcp_f32_e32 v181, v175
	v_rcp_f32_e32 v175, v182
	v_mul_f32_e32 v139, 0xbfb8aa3b, v139
	v_exp_f32_e32 v139, v139
	v_pk_mul_f32 v[178:179], v[182:183], v[180:181]
	v_add_f32_e32 v181, v24, v140
	v_mul_f32_e32 v181, 0xbfb8aa3b, v181
	v_exp_f32_e32 v181, v181
	v_add_f32_e32 v183, v25, v141
	v_mul_f32_e32 v183, 0xbfb8aa3b, v183
	v_exp_f32_e32 v183, v183
	v_add_f32_e32 v181, 1.0, v181
	v_add_f32_e32 v180, v32, v144
	v_rcp_f32_e32 v182, v181
	v_add_f32_e32 v181, v33, v145
	v_mul_f32_e32 v180, 0xbfb8aa3b, v180
	v_mul_f32_e32 v181, 0xbfb8aa3b, v181
	v_exp_f32_e32 v180, v180
	v_exp_f32_e32 v181, v181
	v_add_f32_e32 v183, 1.0, v183
	v_rcp_f32_e32 v183, v183
	v_add_f32_e32 v143, v15, v143
	v_pk_add_f32 v[180:181], v[180:181], 1.0 op_sel_hi:[1,0]
	v_mul_f32_e32 v143, 0xbfb8aa3b, v143
	v_pk_mul_f32 v[184:185], v[180:181], v[182:183]
	v_rcp_f32_e32 v197, v181
	v_add_f32_e32 v181, v18, v130
	v_mul_f32_e32 v181, 0xbfb8aa3b, v181
	v_exp_f32_e32 v181, v181
	v_add_f32_e32 v183, v19, v131
	v_mul_f32_e32 v183, 0xbfb8aa3b, v183
	v_exp_f32_e32 v183, v183
	v_add_f32_e32 v181, 1.0, v181
	v_rcp_f32_e32 v196, v180
	v_add_f32_e32 v180, v26, v134
	v_rcp_f32_e32 v182, v181
	v_add_f32_e32 v181, v27, v135
	v_mul_f32_e32 v180, 0xbfb8aa3b, v180
	v_mul_f32_e32 v181, 0xbfb8aa3b, v181
	v_exp_f32_e32 v180, v180
	v_exp_f32_e32 v181, v181
	v_add_f32_e32 v183, 1.0, v183
	v_rcp_f32_e32 v183, v183
	v_add_f32_e32 v138, 1.0, v138
	v_pk_add_f32 v[180:181], v[180:181], 1.0 op_sel_hi:[1,0]
	v_exp_f32_e32 v143, v143
	v_pk_mul_f32 v[186:187], v[180:181], v[182:183]
	v_rcp_f32_e32 v199, v181
	v_add_f32_e32 v181, v20, v132
	v_mul_f32_e32 v181, 0xbfb8aa3b, v181
	v_exp_f32_e32 v181, v181
	v_add_f32_e32 v183, v21, v133
	v_mul_f32_e32 v183, 0xbfb8aa3b, v183
	v_exp_f32_e32 v183, v183
	v_add_f32_e32 v181, 1.0, v181
	v_rcp_f32_e32 v198, v180
	v_add_f32_e32 v180, v28, v136
	v_rcp_f32_e32 v182, v181
	v_add_f32_e32 v181, v29, v137
	v_mul_f32_e32 v180, 0xbfb8aa3b, v180
	v_mul_f32_e32 v181, 0xbfb8aa3b, v181
	v_exp_f32_e32 v180, v180
	v_exp_f32_e32 v181, v181
	v_add_f32_e32 v183, 1.0, v183
	v_rcp_f32_e32 v183, v183
	v_add_f32_e32 v139, 1.0, v139
	v_pk_add_f32 v[180:181], v[180:181], 1.0 op_sel_hi:[1,0]
	v_lshl_add_u64 v[194:195], v[176:177], 0, s[0:1]
	v_rcp_f32_e32 v208, v180
	v_pk_mul_f32 v[188:189], v[180:181], v[182:183]
	v_rcp_f32_e32 v183, v181
	s_mov_b32 s0, 0xa0000
	v_rcp_f32_e32 v138, v138
	v_rcp_f32_e32 v139, v139
	v_add_f32_e32 v140, v8, v140
	v_add_f32_e32 v141, v9, v141
	v_add_f32_e32 v130, v2, v130
	v_add_f32_e32 v131, v3, v131
	v_cvt_pk_bf16_f32 v181, v196, v197
	v_add_co_u32_e32 v196, vcc, s0, v176
	v_mul_f32_e32 v140, 0xbfb8aa3b, v140
	v_mul_f32_e32 v141, 0xbfb8aa3b, v141
	v_mul_f32_e32 v130, 0xbfb8aa3b, v130
	v_mul_f32_e32 v131, 0xbfb8aa3b, v131
	v_cvt_pk_bf16_f32 v180, v175, v193
	v_cvt_pk_bf16_f32 v182, v198, v199
	v_cvt_pk_bf16_f32 v183, v208, v183
	v_addc_co_u32_e32 v197, vcc, 0, v177, vcc
	v_exp_f32_e32 v140, v140
	v_exp_f32_e32 v141, v141
	v_exp_f32_e32 v130, v130
	v_exp_f32_e32 v131, v131
	global_store_dwordx4 v[196:197], v[180:183], off sc1 nt
	v_cvt_pk_bf16_f32 v178, v178, v179
	v_cvt_pk_bf16_f32 v179, v184, v185
	v_cvt_pk_bf16_f32 v180, v186, v187
	v_cvt_pk_bf16_f32 v181, v188, v189
	v_pk_add_f32 v[142:143], v[142:143], 1.0 op_sel_hi:[1,0]
	global_store_dwordx4 v[194:195], v[178:181], off offset:2048 sc1 nt
	v_rcp_f32_e32 v175, v142
	v_pk_mul_f32 v[138:139], v[142:143], v[138:139]
	v_rcp_f32_e32 v178, v143
	v_add_f32_e32 v142, v16, v144
	v_add_f32_e32 v143, v17, v145
	v_add_f32_e32 v134, v10, v134
	v_add_f32_e32 v135, v11, v135
	v_mul_f32_e32 v142, 0xbfb8aa3b, v142
	v_mul_f32_e32 v143, 0xbfb8aa3b, v143
	v_mul_f32_e32 v134, 0xbfb8aa3b, v134
	v_mul_f32_e32 v135, 0xbfb8aa3b, v135
	v_exp_f32_e32 v142, v142
	v_add_f32_e32 v140, 1.0, v140
	v_exp_f32_e32 v143, v143
	v_add_f32_e32 v141, 1.0, v141
	v_exp_f32_e32 v134, v134
	v_add_f32_e32 v130, 1.0, v130
	v_exp_f32_e32 v135, v135
	v_add_f32_e32 v131, 1.0, v131
	v_rcp_f32_e32 v140, v140
	v_rcp_f32_e32 v141, v141
	v_rcp_f32_e32 v130, v130
	v_rcp_f32_e32 v131, v131
	v_pk_add_f32 v[142:143], v[142:143], 1.0 op_sel_hi:[1,0]
	v_pk_add_f32 v[134:135], v[134:135], 1.0 op_sel_hi:[1,0]
	v_rcp_f32_e32 v144, v142
	v_pk_mul_f32 v[140:141], v[142:143], v[140:141]
	v_rcp_f32_e32 v145, v143
	v_pk_mul_f32 v[142:143], v[134:135], v[130:131]
	v_add_f32_e32 v131, v4, v132
	v_mul_f32_e32 v131, 0xbfb8aa3b, v131
	v_exp_f32_e32 v131, v131
	v_add_f32_e32 v133, v5, v133
	v_mul_f32_e32 v133, 0xbfb8aa3b, v133
	v_exp_f32_e32 v133, v133
	v_add_f32_e32 v131, 1.0, v131
	v_add_f32_e32 v130, v12, v136
	v_rcp_f32_e32 v132, v131
	v_add_f32_e32 v131, v13, v137
	v_mul_f32_e32 v130, 0xbfb8aa3b, v130
	v_mul_f32_e32 v131, 0xbfb8aa3b, v131
	v_exp_f32_e32 v130, v130
	v_exp_f32_e32 v131, v131
	v_add_f32_e32 v133, 1.0, v133
	v_rcp_f32_e32 v133, v133
	v_rcp_f32_e32 v179, v134
	v_pk_add_f32 v[130:131], v[130:131], 1.0 op_sel_hi:[1,0]
	v_rcp_f32_e32 v180, v135
	v_rcp_f32_e32 v181, v130
	v_pk_mul_f32 v[134:135], v[130:131], v[132:133]
	v_rcp_f32_e32 v133, v131
	s_mov_b64 s[0:1], 0xb0000
	v_lshl_add_u64 v[136:137], v[176:177], 0, s[0:1]
	s_mov_b32 s0, 0xb0000
	v_cvt_pk_bf16_f32 v131, v144, v145
	v_add_co_u32_e32 v144, vcc, s0, v176
	v_cvt_pk_bf16_f32 v130, v175, v178
	v_cvt_pk_bf16_f32 v132, v179, v180
	v_cvt_pk_bf16_f32 v133, v181, v133
	v_addc_co_u32_e32 v145, vcc, 0, v177, vcc
	global_store_dwordx4 v[144:145], v[130:133], off sc1 nt
	s_mov_b64 s[0:1], 0
	s_nop 0
	v_cvt_pk_bf16_f32 v130, v138, v139
	v_cvt_pk_bf16_f32 v131, v140, v141
	v_cvt_pk_bf16_f32 v132, v142, v143
	v_cvt_pk_bf16_f32 v133, v134, v135
	global_store_dwordx4 v[136:137], v[130:133], off offset:2048 sc1 nt
.LBB0_274:
	s_andn2_b64 vcc, exec, s[0:1]
	s_cbranch_vccnz .LBB0_276
	s_lshl_b32 s12, -1, s82
	s_sub_i32 s13, s20, s82
	v_bitop3_b32 v130, v1, s12, v1 bitop3:0x30
	s_lshl_b32 s0, s4, 2
	v_subrev_u32_e32 v140, s3, v174
	v_lshlrev_b32_e32 v130, s13, v130
	s_or_b32 s4, s0, s44
	v_ashrrev_i32_e32 v131, s82, v140
	v_add_u32_e32 v141, s3, v130
	s_lshl_b64 s[0:1], s[4:5], 23
	v_add_u32_e32 v130, v141, v131
	v_ashrrev_i32_e32 v131, 31, v130
	s_add_u32 s0, s96, s0
	s_addc_u32 s1, s97, s1
	v_lshlrev_b64 v[130:131], 8, v[130:131]
	v_lshl_add_u64 v[130:131], s[0:1], 0, v[130:131]
	v_lshlrev_b32_e32 v134, 1, v154
	v_mov_b32_e32 v135, v0
	v_lshl_add_u64 v[136:137], v[130:131], 0, v[134:135]
	s_mov_b64 s[38:39], 0x5000080
	s_mov_b32 s4, 0x5000000
	v_lshl_add_u64 v[138:139], v[136:137], 0, s[38:39]
	v_add_co_u32_e32 v136, vcc, s4, v136
	v_cvt_pk_bf16_f32 v130, v126, v127
	v_cvt_pk_bf16_f32 v131, v128, v129
	v_cvt_pk_bf16_f32 v132, v122, v123
	v_cvt_pk_bf16_f32 v133, v124, v125
	v_addc_co_u32_e32 v137, vcc, 0, v137, vcc
	global_store_dwordx4 v[136:137], v[130:133], off offset:128 sc1 nt
	s_nop 1
	v_cvt_pk_bf16_f32 v130, v118, v119
	v_cvt_pk_bf16_f32 v131, v120, v121
	v_cvt_pk_bf16_f32 v132, v114, v115
	v_cvt_pk_bf16_f32 v133, v116, v117
	global_store_dwordx4 v[138:139], v[130:133], off offset:64 sc1 nt
	s_nop 1
	v_or_b32_e32 v130, 16, v140
	v_bitop3_b32 v131, v140, s12, 16 bitop3:0x32
	v_lshlrev_b32_e32 v131, s13, v131
	v_ashrrev_i32_e32 v130, s82, v130
	v_add3_u32 v130, v130, s3, v131
	v_ashrrev_i32_e32 v131, 31, v130
	v_lshlrev_b64 v[130:131], 8, v[130:131]
	v_lshl_add_u64 v[130:131], s[0:1], 0, v[130:131]
	v_lshl_add_u64 v[136:137], v[130:131], 0, v[134:135]
	v_lshl_add_u64 v[138:139], v[136:137], 0, s[38:39]
	v_add_co_u32_e32 v136, vcc, s4, v136
	v_cvt_pk_bf16_f32 v130, v110, v111
	v_cvt_pk_bf16_f32 v131, v112, v113
	v_cvt_pk_bf16_f32 v132, v106, v107
	v_cvt_pk_bf16_f32 v133, v108, v109
	v_addc_co_u32_e32 v137, vcc, 0, v137, vcc
	global_store_dwordx4 v[136:137], v[130:133], off offset:128 sc1 nt
	s_nop 1
	v_cvt_pk_bf16_f32 v130, v102, v103
	v_cvt_pk_bf16_f32 v131, v104, v105
	v_cvt_pk_bf16_f32 v132, v98, v99
	v_cvt_pk_bf16_f32 v133, v100, v101
	global_store_dwordx4 v[138:139], v[130:133], off offset:64 sc1 nt
	s_nop 1
	v_or_b32_e32 v130, 32, v140
	v_bitop3_b32 v131, v140, s12, 32 bitop3:0x32
	v_lshlrev_b32_e32 v131, s13, v131
	v_ashrrev_i32_e32 v130, s82, v130
	v_add3_u32 v130, v130, s3, v131
	v_ashrrev_i32_e32 v131, 31, v130
	v_lshlrev_b64 v[130:131], 8, v[130:131]
	v_lshl_add_u64 v[130:131], s[0:1], 0, v[130:131]
	v_lshl_add_u64 v[136:137], v[130:131], 0, v[134:135]
	v_lshl_add_u64 v[138:139], v[136:137], 0, s[38:39]
	v_add_co_u32_e32 v136, vcc, s4, v136
	v_cvt_pk_bf16_f32 v130, v94, v95
	v_cvt_pk_bf16_f32 v131, v96, v97
	v_cvt_pk_bf16_f32 v132, v90, v91
	v_cvt_pk_bf16_f32 v133, v92, v93
	v_addc_co_u32_e32 v137, vcc, 0, v137, vcc
	global_store_dwordx4 v[136:137], v[130:133], off offset:128 sc1 nt
	s_nop 1
	v_cvt_pk_bf16_f32 v130, v86, v87
	v_cvt_pk_bf16_f32 v131, v88, v89
	v_cvt_pk_bf16_f32 v132, v82, v83
	v_cvt_pk_bf16_f32 v133, v84, v85
	global_store_dwordx4 v[138:139], v[130:133], off offset:64 sc1 nt
	s_nop 1
	v_or_b32_e32 v130, 48, v140
	v_bitop3_b32 v131, v140, s12, 48 bitop3:0x32
	v_lshlrev_b32_e32 v131, s13, v131
	v_ashrrev_i32_e32 v130, s82, v130
	v_add3_u32 v130, v130, s3, v131
	v_ashrrev_i32_e32 v131, 31, v130
	v_lshlrev_b64 v[130:131], 8, v[130:131]
	v_lshl_add_u64 v[130:131], s[0:1], 0, v[130:131]
	v_lshl_add_u64 v[136:137], v[130:131], 0, v[134:135]
	v_lshl_add_u64 v[138:139], v[136:137], 0, s[38:39]
	v_add_co_u32_e32 v136, vcc, s4, v136
	v_cvt_pk_bf16_f32 v130, v78, v79
	v_cvt_pk_bf16_f32 v131, v80, v81
	v_cvt_pk_bf16_f32 v132, v74, v75
	v_cvt_pk_bf16_f32 v133, v76, v77
	v_addc_co_u32_e32 v137, vcc, 0, v137, vcc
	global_store_dwordx4 v[136:137], v[130:133], off offset:128 sc1 nt
	s_nop 1
	v_cvt_pk_bf16_f32 v130, v70, v71
	v_cvt_pk_bf16_f32 v131, v72, v73
	v_cvt_pk_bf16_f32 v132, v66, v67
	v_cvt_pk_bf16_f32 v133, v68, v69
	global_store_dwordx4 v[138:139], v[130:133], off offset:64 sc1 nt
	s_nop 1
	v_add_u32_e32 v130, 0x80, v140
	v_ashrrev_i32_e32 v130, s82, v130
	v_add_u32_e32 v130, v130, v141
	v_ashrrev_i32_e32 v131, 31, v130
	v_lshlrev_b64 v[130:131], 8, v[130:131]
	v_lshl_add_u64 v[130:131], s[0:1], 0, v[130:131]
	v_lshl_add_u64 v[136:137], v[130:131], 0, v[134:135]
	v_lshl_add_u64 v[138:139], v[136:137], 0, s[38:39]
	v_add_co_u32_e32 v136, vcc, s4, v136
	v_cvt_pk_bf16_f32 v130, v62, v63
	v_cvt_pk_bf16_f32 v131, v64, v65
	v_cvt_pk_bf16_f32 v132, v58, v59
	v_cvt_pk_bf16_f32 v133, v60, v61
	v_addc_co_u32_e32 v137, vcc, 0, v137, vcc
	global_store_dwordx4 v[136:137], v[130:133], off offset:128 sc1 nt
	s_nop 1
	v_cvt_pk_bf16_f32 v130, v54, v55
	v_cvt_pk_bf16_f32 v131, v56, v57
	v_cvt_pk_bf16_f32 v132, v50, v51
	v_cvt_pk_bf16_f32 v133, v52, v53
	global_store_dwordx4 v[138:139], v[130:133], off offset:64 sc1 nt
	s_nop 1
	v_add_u32_e32 v130, 0x90, v140
	v_bitop3_b32 v131, v130, s12, v130 bitop3:0x30
	v_lshlrev_b32_e32 v131, s13, v131
	v_ashrrev_i32_e32 v130, s82, v130
	v_add3_u32 v130, v130, s3, v131
	v_ashrrev_i32_e32 v131, 31, v130
	v_lshlrev_b64 v[130:131], 8, v[130:131]
	v_lshl_add_u64 v[130:131], s[0:1], 0, v[130:131]
	v_lshl_add_u64 v[136:137], v[130:131], 0, v[134:135]
	v_lshl_add_u64 v[138:139], v[136:137], 0, s[38:39]
	v_add_co_u32_e32 v136, vcc, s4, v136
	v_cvt_pk_bf16_f32 v130, v46, v47
	v_cvt_pk_bf16_f32 v131, v48, v49
	v_cvt_pk_bf16_f32 v132, v42, v43
	v_cvt_pk_bf16_f32 v133, v44, v45
	v_addc_co_u32_e32 v137, vcc, 0, v137, vcc
	global_store_dwordx4 v[136:137], v[130:133], off offset:128 sc1 nt
	s_nop 1
	v_cvt_pk_bf16_f32 v130, v38, v39
	v_cvt_pk_bf16_f32 v131, v40, v41
	v_cvt_pk_bf16_f32 v132, v34, v35
	v_cvt_pk_bf16_f32 v133, v36, v37
	global_store_dwordx4 v[138:139], v[130:133], off offset:64 sc1 nt
	s_nop 1
	v_add_u32_e32 v130, 0xa0, v140
	v_bitop3_b32 v131, v130, s12, v130 bitop3:0x30
	v_lshlrev_b32_e32 v131, s13, v131
	v_ashrrev_i32_e32 v130, s82, v130
	v_add3_u32 v130, v130, s3, v131
	v_ashrrev_i32_e32 v131, 31, v130
	v_lshlrev_b64 v[130:131], 8, v[130:131]
	v_lshl_add_u64 v[130:131], s[0:1], 0, v[130:131]
	v_lshl_add_u64 v[136:137], v[130:131], 0, v[134:135]
	v_lshl_add_u64 v[138:139], v[136:137], 0, s[38:39]
	v_add_co_u32_e32 v136, vcc, s4, v136
	v_cvt_pk_bf16_f32 v130, v30, v31
	v_cvt_pk_bf16_f32 v131, v32, v33
	v_cvt_pk_bf16_f32 v132, v26, v27
	v_cvt_pk_bf16_f32 v133, v28, v29
	v_addc_co_u32_e32 v137, vcc, 0, v137, vcc
	global_store_dwordx4 v[136:137], v[130:133], off offset:128 sc1 nt
	s_nop 1
	v_cvt_pk_bf16_f32 v130, v22, v23
	v_cvt_pk_bf16_f32 v131, v24, v25
	v_cvt_pk_bf16_f32 v132, v18, v19
	v_cvt_pk_bf16_f32 v133, v20, v21
	global_store_dwordx4 v[138:139], v[130:133], off offset:64 sc1 nt
	s_nop 1
	v_add_u32_e32 v130, 0xb0, v140
	v_bitop3_b32 v131, v130, s12, v130 bitop3:0x30
	v_lshlrev_b32_e32 v131, s13, v131
	v_ashrrev_i32_e32 v130, s82, v130
	v_add3_u32 v130, v130, s3, v131
	v_ashrrev_i32_e32 v131, 31, v130
	v_lshlrev_b64 v[130:131], 8, v[130:131]
	v_lshl_add_u64 v[130:131], s[0:1], 0, v[130:131]
	v_lshl_add_u64 v[134:135], v[130:131], 0, v[134:135]
	v_lshl_add_u64 v[136:137], v[134:135], 0, s[38:39]
	v_add_co_u32_e32 v134, vcc, s4, v134
	v_cvt_pk_bf16_f32 v130, v14, v15
	v_cvt_pk_bf16_f32 v131, v16, v17
	v_cvt_pk_bf16_f32 v132, v10, v11
	v_cvt_pk_bf16_f32 v133, v12, v13
	v_addc_co_u32_e32 v135, vcc, 0, v135, vcc
	global_store_dwordx4 v[134:135], v[130:133], off offset:128 sc1 nt
	s_nop 1
	v_cvt_pk_bf16_f32 v130, v6, v7
	v_cvt_pk_bf16_f32 v131, v8, v9
	v_cvt_pk_bf16_f32 v132, v2, v3
	v_cvt_pk_bf16_f32 v133, v4, v5
	global_store_dwordx4 v[136:137], v[130:133], off offset:64 sc1 nt

.LBB0_283:
	s_waitcnt lgkmcnt(0)
	v_add_f32_e32 v177, v185, v186
	v_fmamk_f32 v177, v177, 0x3c800000, v201
	v_rsq_f32_e32 v186, v177
	v_cndmask_b32_e64 v188, 1.0, v205, s[38:39]
	s_waitcnt vmcnt(0)
	v_pk_mul_f32 v[144:145], v[188:189], v[144:145] op_sel_hi:[0,1]
	v_pk_mul_f32 v[142:143], v[188:189], v[142:143] op_sel_hi:[0,1]
	v_pk_mul_f32 v[140:141], v[188:189], v[140:141] op_sel_hi:[0,1]
	v_pk_mul_f32 v[138:139], v[188:189], v[138:139] op_sel_hi:[0,1]
	v_pk_mul_f32 v[128:129], v[128:129], v[186:187] op_sel_hi:[1,0]
	v_pk_mul_f32 v[126:127], v[126:127], v[186:187] op_sel_hi:[1,0]
	v_pk_mul_f32 v[124:125], v[124:125], v[186:187] op_sel_hi:[1,0]
	v_pk_mul_f32 v[122:123], v[122:123], v[186:187] op_sel_hi:[1,0]
	v_pk_mul_f32 v[136:137], v[188:189], v[136:137] op_sel_hi:[0,1]
	v_pk_mul_f32 v[134:135], v[188:189], v[134:135] op_sel_hi:[0,1]
	v_pk_mul_f32 v[132:133], v[188:189], v[132:133] op_sel_hi:[0,1]
	v_pk_mul_f32 v[130:131], v[188:189], v[130:131] op_sel_hi:[0,1]
	v_pk_mul_f32 v[128:129], v[144:145], v[128:129]
	v_pk_mul_f32 v[126:127], v[142:143], v[126:127]
	v_pk_mul_f32 v[188:189], v[140:141], v[124:125]
	v_pk_mul_f32 v[124:125], v[138:139], v[122:123]
	v_cvt_pk_bf16_f32 v122, v126, v127
	v_cvt_pk_bf16_f32 v123, v128, v129
	v_cvt_pk_bf16_f32 v124, v124, v125
	v_cvt_pk_bf16_f32 v125, v188, v189
	v_pk_mul_f32 v[120:121], v[120:121], v[186:187] op_sel_hi:[1,0]
	v_pk_mul_f32 v[118:119], v[118:119], v[186:187] op_sel_hi:[1,0]
	v_pk_mul_f32 v[116:117], v[116:117], v[186:187] op_sel_hi:[1,0]
	v_pk_mul_f32 v[114:115], v[114:115], v[186:187] op_sel_hi:[1,0]
	global_store_dwordx4 v[180:181], v[122:125], off sc1 nt
	v_pk_mul_f32 v[120:121], v[136:137], v[120:121]
	v_pk_mul_f32 v[118:119], v[134:135], v[118:119]
	v_pk_mul_f32 v[122:123], v[132:133], v[116:117]
	v_pk_mul_f32 v[116:117], v[130:131], v[114:115]
	v_cvt_pk_bf16_f32 v114, v118, v119
	v_cvt_pk_bf16_f32 v115, v120, v121
	v_cvt_pk_bf16_f32 v116, v116, v117
	v_cvt_pk_bf16_f32 v117, v122, v123
	global_store_dwordx4 v[180:181], v[114:117], off offset:64 sc1 nt
	s_mov_b64 s[20:21], -1
	s_andn2_b64 vcc, exec, s[12:13]
	v_mul_f32_e32 v114, v111, v111
	v_mul_f32_e32 v115, v113, v113
	v_fmac_f32_e32 v114, v110, v110
	v_fmac_f32_e32 v115, v112, v112
	v_add_f32_e32 v114, v114, v115
	v_mul_f32_e32 v115, v107, v107
	v_mul_f32_e32 v116, v109, v109
	v_fmac_f32_e32 v115, v106, v106
	v_fmac_f32_e32 v116, v108, v108
	v_add_f32_e32 v115, v115, v116
	v_add_f32_e32 v114, v115, v114
	v_mul_f32_e32 v115, v103, v103
	v_mul_f32_e32 v116, v105, v105
	v_fmac_f32_e32 v115, v102, v102
	v_fmac_f32_e32 v116, v104, v104
	v_add_f32_e32 v115, v115, v116
	v_add_f32_e32 v114, v115, v114
	v_mul_f32_e32 v115, v99, v99
	v_mul_f32_e32 v116, v101, v101
	v_fmac_f32_e32 v115, v98, v98
	v_fmac_f32_e32 v116, v100, v100
	v_add_f32_e32 v115, v115, v116
	v_add_f32_e32 v114, v115, v114
	ds_bpermute_b32 v115, v183, v114
	s_mov_b64 s[48:49], s[58:59]
	s_waitcnt lgkmcnt(0)
	v_add_f32_e32 v116, v114, v115
	ds_bpermute_b32 v117, v182, v116
	v_cndmask_b32_e64 v114, 0, 1, s[12:13]
	v_cmp_ne_u32_e64 s[38:39], 1, v114
	s_cbranch_vccnz .LBB0_285
	v_or_b32_e32 v114, 16, v175
	v_bitop3_b32 v115, v175, s4, 16 bitop3:0xc8
	v_lshlrev_b32_e32 v115, s26, v115
	v_ashrrev_i32_e32 v114, s82, v114
	v_add3_u32 v114, v114, s3, v115
	v_ashrrev_i32_e32 v115, 31, v114
	s_add_u32 s12, s98, s0
	s_addc_u32 s13, s99, s1
	v_lshlrev_b64 v[114:115], 8, v[114:115]
	v_lshl_add_u64 v[114:115], s[12:13], 0, v[114:115]
	v_mov_b32_e32 v177, v0
	v_lshl_add_u64 v[114:115], v[114:115], 0, v[176:177]
	s_mov_b64 s[20:21], 0

.LBB0_287:
	s_waitcnt lgkmcnt(0)
	v_add_f32_e32 v116, v116, v117
	v_fmamk_f32 v116, v116, 0x3c800000, v201
	v_rsq_f32_e32 v116, v116
	s_and_b64 vcc, exec, s[38:39]
	s_mov_b64 s[12:13], -1
	v_pk_mul_f32 v[112:113], v[112:113], v[116:117] op_sel_hi:[1,0]
	v_pk_mul_f32 v[110:111], v[110:111], v[116:117] op_sel_hi:[1,0]
	v_pk_mul_f32 v[108:109], v[108:109], v[116:117] op_sel_hi:[1,0]
	v_pk_mul_f32 v[106:107], v[106:107], v[116:117] op_sel_hi:[1,0]
	v_pk_mul_f32 v[112:113], v[144:145], v[112:113]
	v_pk_mul_f32 v[110:111], v[142:143], v[110:111]
	v_pk_mul_f32 v[118:119], v[140:141], v[108:109]
	v_pk_mul_f32 v[108:109], v[138:139], v[106:107]
	v_pk_mul_f32 v[102:103], v[102:103], v[116:117] op_sel_hi:[1,0]
	v_cvt_pk_bf16_f32 v106, v110, v111
	v_cvt_pk_bf16_f32 v107, v112, v113
	v_cvt_pk_bf16_f32 v108, v108, v109
	v_cvt_pk_bf16_f32 v109, v118, v119
	v_pk_mul_f32 v[102:103], v[134:135], v[102:103]
	v_pk_mul_f32 v[100:101], v[100:101], v[116:117] op_sel_hi:[1,0]
	v_pk_mul_f32 v[98:99], v[98:99], v[116:117] op_sel_hi:[1,0]
	global_store_dwordx4 v[114:115], v[106:109], off sc1 nt
	v_pk_mul_f32 v[104:105], v[104:105], v[116:117] op_sel_hi:[1,0]
	s_nop 0
	v_pk_mul_f32 v[106:107], v[132:133], v[100:101]
	v_pk_mul_f32 v[100:101], v[130:131], v[98:99]
	v_cvt_pk_bf16_f32 v98, v102, v103
	v_mul_f32_e32 v99, v95, v95
	v_mul_f32_e32 v102, v97, v97
	v_fmac_f32_e32 v99, v94, v94
	v_fmac_f32_e32 v102, v96, v96
	v_add_f32_e32 v99, v99, v102
	v_mul_f32_e32 v102, v91, v91
	v_mul_f32_e32 v103, v93, v93
	v_fmac_f32_e32 v102, v90, v90
	v_fmac_f32_e32 v103, v92, v92
	v_add_f32_e32 v102, v102, v103
	v_add_f32_e32 v99, v102, v99
	v_mul_f32_e32 v102, v87, v87
	v_mul_f32_e32 v103, v89, v89
	v_fmac_f32_e32 v102, v86, v86
	v_fmac_f32_e32 v103, v88, v88
	v_add_f32_e32 v102, v102, v103
	v_add_f32_e32 v99, v102, v99
	v_mul_f32_e32 v102, v83, v83
	v_mul_f32_e32 v103, v85, v85
	v_fmac_f32_e32 v102, v82, v82
	v_fmac_f32_e32 v103, v84, v84
	v_add_f32_e32 v102, v102, v103
	v_add_f32_e32 v102, v102, v99
	ds_bpermute_b32 v103, v183, v102
	v_pk_mul_f32 v[104:105], v[136:137], v[104:105]
	v_cvt_pk_bf16_f32 v100, v100, v101
	v_cvt_pk_bf16_f32 v99, v104, v105
	v_cvt_pk_bf16_f32 v101, v106, v107
	global_store_dwordx4 v[114:115], v[98:101], off offset:64 sc1 nt
	s_waitcnt lgkmcnt(0)
	s_nop 0
	v_add_f32_e32 v100, v102, v103
	ds_bpermute_b32 v101, v182, v100
	s_cbranch_vccnz .LBB0_289
	v_or_b32_e32 v98, 32, v175
	v_bitop3_b32 v99, v175, s4, 32 bitop3:0xc8
	v_lshlrev_b32_e32 v99, s26, v99
	v_ashrrev_i32_e32 v98, s82, v98
	v_add3_u32 v98, v98, s3, v99
	v_ashrrev_i32_e32 v99, 31, v98
	s_add_u32 s12, s98, s0
	s_addc_u32 s13, s99, s1
	v_lshlrev_b64 v[98:99], 8, v[98:99]
	v_lshl_add_u64 v[98:99], s[12:13], 0, v[98:99]
	v_mov_b32_e32 v177, v0
	v_lshl_add_u64 v[98:99], v[98:99], 0, v[176:177]
	s_mov_b64 s[12:13], 0

.LBB0_291:
	s_waitcnt lgkmcnt(0)
	v_add_f32_e32 v100, v100, v101
	v_fmamk_f32 v100, v100, 0x3c800000, v201
	v_rsq_f32_e32 v100, v100
	s_and_b64 vcc, exec, s[38:39]
	s_mov_b64 s[12:13], -1
	v_pk_mul_f32 v[96:97], v[96:97], v[100:101] op_sel_hi:[1,0]
	v_pk_mul_f32 v[94:95], v[94:95], v[100:101] op_sel_hi:[1,0]
	v_pk_mul_f32 v[92:93], v[92:93], v[100:101] op_sel_hi:[1,0]
	v_pk_mul_f32 v[90:91], v[90:91], v[100:101] op_sel_hi:[1,0]
	v_pk_mul_f32 v[96:97], v[144:145], v[96:97]
	v_pk_mul_f32 v[94:95], v[142:143], v[94:95]
	v_pk_mul_f32 v[102:103], v[140:141], v[92:93]
	v_pk_mul_f32 v[92:93], v[138:139], v[90:91]
	v_pk_mul_f32 v[86:87], v[86:87], v[100:101] op_sel_hi:[1,0]
	v_cvt_pk_bf16_f32 v90, v94, v95
	v_cvt_pk_bf16_f32 v91, v96, v97
	v_cvt_pk_bf16_f32 v92, v92, v93
	v_cvt_pk_bf16_f32 v93, v102, v103
	v_pk_mul_f32 v[86:87], v[134:135], v[86:87]
	v_pk_mul_f32 v[84:85], v[84:85], v[100:101] op_sel_hi:[1,0]
	v_pk_mul_f32 v[82:83], v[82:83], v[100:101] op_sel_hi:[1,0]
	global_store_dwordx4 v[98:99], v[90:93], off sc1 nt
	v_pk_mul_f32 v[88:89], v[88:89], v[100:101] op_sel_hi:[1,0]
	s_nop 0
	v_pk_mul_f32 v[90:91], v[132:133], v[84:85]
	v_pk_mul_f32 v[84:85], v[130:131], v[82:83]
	v_cvt_pk_bf16_f32 v82, v86, v87
	v_mul_f32_e32 v83, v79, v79
	v_mul_f32_e32 v86, v81, v81
	v_fmac_f32_e32 v83, v78, v78
	v_fmac_f32_e32 v86, v80, v80
	v_add_f32_e32 v83, v83, v86
	v_mul_f32_e32 v86, v75, v75
	v_mul_f32_e32 v87, v77, v77
	v_fmac_f32_e32 v86, v74, v74
	v_fmac_f32_e32 v87, v76, v76
	v_add_f32_e32 v86, v86, v87
	v_add_f32_e32 v83, v86, v83
	v_mul_f32_e32 v86, v71, v71
	v_mul_f32_e32 v87, v73, v73
	v_fmac_f32_e32 v86, v70, v70
	v_fmac_f32_e32 v87, v72, v72
	v_add_f32_e32 v86, v86, v87
	v_add_f32_e32 v83, v86, v83
	v_mul_f32_e32 v86, v67, v67
	v_mul_f32_e32 v87, v69, v69
	v_fmac_f32_e32 v86, v66, v66
	v_fmac_f32_e32 v87, v68, v68
	v_add_f32_e32 v86, v86, v87
	v_add_f32_e32 v86, v86, v83
	ds_bpermute_b32 v87, v183, v86
	v_pk_mul_f32 v[88:89], v[136:137], v[88:89]
	v_cvt_pk_bf16_f32 v84, v84, v85
	v_cvt_pk_bf16_f32 v83, v88, v89
	v_cvt_pk_bf16_f32 v85, v90, v91
	global_store_dwordx4 v[98:99], v[82:85], off offset:64 sc1 nt
	s_waitcnt lgkmcnt(0)
	s_nop 0
	v_add_f32_e32 v84, v86, v87
	ds_bpermute_b32 v85, v182, v84
	s_cbranch_vccnz .LBB0_293
	v_or_b32_e32 v82, 48, v175
	v_bitop3_b32 v83, v175, s4, 48 bitop3:0xc8
	v_lshlrev_b32_e32 v83, s26, v83
	v_ashrrev_i32_e32 v82, s82, v82
	v_add3_u32 v82, v82, s3, v83
	v_ashrrev_i32_e32 v83, 31, v82
	s_add_u32 s12, s98, s0
	s_addc_u32 s13, s99, s1
	v_lshlrev_b64 v[82:83], 8, v[82:83]
	v_lshl_add_u64 v[82:83], s[12:13], 0, v[82:83]
	v_mov_b32_e32 v177, v0
	v_lshl_add_u64 v[82:83], v[82:83], 0, v[176:177]
	s_mov_b64 s[12:13], 0

.LBB0_295:
	s_waitcnt lgkmcnt(0)
	v_add_f32_e32 v84, v84, v85
	v_fmamk_f32 v84, v84, 0x3c800000, v201
	v_rsq_f32_e32 v84, v84
	s_and_b64 vcc, exec, s[38:39]
	s_mov_b64 s[12:13], -1
	v_pk_mul_f32 v[80:81], v[80:81], v[84:85] op_sel_hi:[1,0]
	v_pk_mul_f32 v[78:79], v[78:79], v[84:85] op_sel_hi:[1,0]
	v_pk_mul_f32 v[76:77], v[76:77], v[84:85] op_sel_hi:[1,0]
	v_pk_mul_f32 v[74:75], v[74:75], v[84:85] op_sel_hi:[1,0]
	v_pk_mul_f32 v[80:81], v[144:145], v[80:81]
	v_pk_mul_f32 v[78:79], v[142:143], v[78:79]
	v_pk_mul_f32 v[86:87], v[140:141], v[76:77]
	v_pk_mul_f32 v[76:77], v[138:139], v[74:75]
	v_pk_mul_f32 v[70:71], v[70:71], v[84:85] op_sel_hi:[1,0]
	v_cvt_pk_bf16_f32 v74, v78, v79
	v_cvt_pk_bf16_f32 v75, v80, v81
	v_cvt_pk_bf16_f32 v76, v76, v77
	v_cvt_pk_bf16_f32 v77, v86, v87
	v_pk_mul_f32 v[70:71], v[134:135], v[70:71]
	v_pk_mul_f32 v[68:69], v[68:69], v[84:85] op_sel_hi:[1,0]
	v_pk_mul_f32 v[66:67], v[66:67], v[84:85] op_sel_hi:[1,0]
	global_store_dwordx4 v[82:83], v[74:77], off sc1 nt
	v_pk_mul_f32 v[72:73], v[72:73], v[84:85] op_sel_hi:[1,0]
	s_nop 0
	v_pk_mul_f32 v[74:75], v[132:133], v[68:69]
	v_pk_mul_f32 v[68:69], v[130:131], v[66:67]
	v_cvt_pk_bf16_f32 v66, v70, v71
	v_mul_f32_e32 v67, v63, v63
	v_mul_f32_e32 v70, v65, v65
	v_fmac_f32_e32 v67, v62, v62
	v_fmac_f32_e32 v70, v64, v64
	v_add_f32_e32 v67, v67, v70
	v_mul_f32_e32 v70, v59, v59
	v_mul_f32_e32 v71, v61, v61
	v_fmac_f32_e32 v70, v58, v58
	v_fmac_f32_e32 v71, v60, v60
	v_add_f32_e32 v70, v70, v71
	v_add_f32_e32 v67, v70, v67
	v_mul_f32_e32 v70, v55, v55
	v_mul_f32_e32 v71, v57, v57
	v_fmac_f32_e32 v70, v54, v54
	v_fmac_f32_e32 v71, v56, v56
	v_add_f32_e32 v70, v70, v71
	v_add_f32_e32 v67, v70, v67
	v_mul_f32_e32 v70, v51, v51
	v_mul_f32_e32 v71, v53, v53
	v_fmac_f32_e32 v70, v50, v50
	v_fmac_f32_e32 v71, v52, v52
	v_add_f32_e32 v70, v70, v71
	v_add_f32_e32 v70, v70, v67
	ds_bpermute_b32 v71, v183, v70
	v_pk_mul_f32 v[72:73], v[136:137], v[72:73]
	v_cvt_pk_bf16_f32 v68, v68, v69
	v_cvt_pk_bf16_f32 v67, v72, v73
	v_cvt_pk_bf16_f32 v69, v74, v75
	global_store_dwordx4 v[82:83], v[66:69], off offset:64 sc1 nt
	s_waitcnt lgkmcnt(0)
	s_nop 0
	v_add_f32_e32 v68, v70, v71
	ds_bpermute_b32 v69, v182, v68
	s_cbranch_vccnz .LBB0_297
	v_add_u32_e32 v66, 0x80, v175
	v_ashrrev_i32_e32 v66, s82, v66
	v_add3_u32 v66, v184, s3, v66
	v_ashrrev_i32_e32 v67, 31, v66
	s_add_u32 s12, s98, s0
	s_addc_u32 s13, s99, s1
	v_lshlrev_b64 v[66:67], 8, v[66:67]
	v_lshl_add_u64 v[66:67], s[12:13], 0, v[66:67]
	v_mov_b32_e32 v177, v0
	v_lshl_add_u64 v[66:67], v[66:67], 0, v[176:177]
	s_mov_b64 s[12:13], 0

.LBB0_299:
	s_waitcnt lgkmcnt(0)
	v_add_f32_e32 v68, v68, v69
	v_fmamk_f32 v68, v68, 0x3c800000, v201
	v_rsq_f32_e32 v68, v68
	s_and_b64 vcc, exec, s[38:39]
	s_mov_b64 s[12:13], -1
	v_pk_mul_f32 v[64:65], v[64:65], v[68:69] op_sel_hi:[1,0]
	v_pk_mul_f32 v[62:63], v[62:63], v[68:69] op_sel_hi:[1,0]
	v_pk_mul_f32 v[60:61], v[60:61], v[68:69] op_sel_hi:[1,0]
	v_pk_mul_f32 v[58:59], v[58:59], v[68:69] op_sel_hi:[1,0]
	v_pk_mul_f32 v[64:65], v[144:145], v[64:65]
	v_pk_mul_f32 v[62:63], v[142:143], v[62:63]
	v_pk_mul_f32 v[70:71], v[140:141], v[60:61]
	v_pk_mul_f32 v[60:61], v[138:139], v[58:59]
	v_pk_mul_f32 v[54:55], v[54:55], v[68:69] op_sel_hi:[1,0]
	v_cvt_pk_bf16_f32 v58, v62, v63
	v_cvt_pk_bf16_f32 v59, v64, v65
	v_cvt_pk_bf16_f32 v60, v60, v61
	v_cvt_pk_bf16_f32 v61, v70, v71
	v_pk_mul_f32 v[54:55], v[134:135], v[54:55]
	v_pk_mul_f32 v[52:53], v[52:53], v[68:69] op_sel_hi:[1,0]
	v_pk_mul_f32 v[50:51], v[50:51], v[68:69] op_sel_hi:[1,0]
	global_store_dwordx4 v[66:67], v[58:61], off sc1 nt
	v_pk_mul_f32 v[56:57], v[56:57], v[68:69] op_sel_hi:[1,0]
	s_nop 0
	v_pk_mul_f32 v[58:59], v[132:133], v[52:53]
	v_pk_mul_f32 v[52:53], v[130:131], v[50:51]
	v_cvt_pk_bf16_f32 v50, v54, v55
	v_mul_f32_e32 v51, v47, v47
	v_mul_f32_e32 v54, v49, v49
	v_fmac_f32_e32 v51, v46, v46
	v_fmac_f32_e32 v54, v48, v48
	v_add_f32_e32 v51, v51, v54
	v_mul_f32_e32 v54, v43, v43
	v_mul_f32_e32 v55, v45, v45
	v_fmac_f32_e32 v54, v42, v42
	v_fmac_f32_e32 v55, v44, v44
	v_add_f32_e32 v54, v54, v55
	v_add_f32_e32 v51, v54, v51
	v_mul_f32_e32 v54, v39, v39
	v_mul_f32_e32 v55, v41, v41
	v_fmac_f32_e32 v54, v38, v38
	v_fmac_f32_e32 v55, v40, v40
	v_add_f32_e32 v54, v54, v55
	v_add_f32_e32 v51, v54, v51
	v_mul_f32_e32 v54, v35, v35
	v_mul_f32_e32 v55, v37, v37
	v_fmac_f32_e32 v54, v34, v34
	v_fmac_f32_e32 v55, v36, v36
	v_add_f32_e32 v54, v54, v55
	v_add_f32_e32 v54, v54, v51
	ds_bpermute_b32 v55, v183, v54
	v_pk_mul_f32 v[56:57], v[136:137], v[56:57]
	v_cvt_pk_bf16_f32 v52, v52, v53
	v_cvt_pk_bf16_f32 v51, v56, v57
	v_cvt_pk_bf16_f32 v53, v58, v59
	global_store_dwordx4 v[66:67], v[50:53], off offset:64 sc1 nt
	s_waitcnt lgkmcnt(0)
	s_nop 0
	v_add_f32_e32 v52, v54, v55
	ds_bpermute_b32 v53, v182, v52
	s_cbranch_vccnz .LBB0_301
	v_add_u32_e32 v50, 0x90, v175
	v_and_b32_e32 v51, s4, v50
	v_lshlrev_b32_e32 v51, s26, v51
	v_ashrrev_i32_e32 v50, s82, v50
	v_add3_u32 v50, v50, s3, v51
	v_ashrrev_i32_e32 v51, 31, v50
	s_add_u32 s12, s98, s0
	s_addc_u32 s13, s99, s1
	v_lshlrev_b64 v[50:51], 8, v[50:51]
	v_lshl_add_u64 v[50:51], s[12:13], 0, v[50:51]
	v_mov_b32_e32 v177, v0
	v_lshl_add_u64 v[50:51], v[50:51], 0, v[176:177]
	s_mov_b64 s[12:13], 0

.LBB0_303:
	s_waitcnt lgkmcnt(0)
	v_add_f32_e32 v52, v52, v53
	v_fmamk_f32 v52, v52, 0x3c800000, v201
	v_rsq_f32_e32 v52, v52
	s_and_b64 vcc, exec, s[38:39]
	s_mov_b64 s[12:13], -1
	v_pk_mul_f32 v[48:49], v[48:49], v[52:53] op_sel_hi:[1,0]
	v_pk_mul_f32 v[46:47], v[46:47], v[52:53] op_sel_hi:[1,0]
	v_pk_mul_f32 v[44:45], v[44:45], v[52:53] op_sel_hi:[1,0]
	v_pk_mul_f32 v[42:43], v[42:43], v[52:53] op_sel_hi:[1,0]
	v_pk_mul_f32 v[48:49], v[144:145], v[48:49]
	v_pk_mul_f32 v[46:47], v[142:143], v[46:47]
	v_pk_mul_f32 v[54:55], v[140:141], v[44:45]
	v_pk_mul_f32 v[44:45], v[138:139], v[42:43]
	v_pk_mul_f32 v[38:39], v[38:39], v[52:53] op_sel_hi:[1,0]
	v_cvt_pk_bf16_f32 v42, v46, v47
	v_cvt_pk_bf16_f32 v43, v48, v49
	v_cvt_pk_bf16_f32 v44, v44, v45
	v_cvt_pk_bf16_f32 v45, v54, v55
	v_pk_mul_f32 v[38:39], v[134:135], v[38:39]
	v_pk_mul_f32 v[36:37], v[36:37], v[52:53] op_sel_hi:[1,0]
	v_pk_mul_f32 v[34:35], v[34:35], v[52:53] op_sel_hi:[1,0]
	global_store_dwordx4 v[50:51], v[42:45], off sc1 nt
	v_pk_mul_f32 v[40:41], v[40:41], v[52:53] op_sel_hi:[1,0]
	s_nop 0
	v_pk_mul_f32 v[42:43], v[132:133], v[36:37]
	v_pk_mul_f32 v[36:37], v[130:131], v[34:35]
	v_cvt_pk_bf16_f32 v34, v38, v39
	v_mul_f32_e32 v35, v31, v31
	v_mul_f32_e32 v38, v33, v33
	v_fmac_f32_e32 v35, v30, v30
	v_fmac_f32_e32 v38, v32, v32
	v_add_f32_e32 v35, v35, v38
	v_mul_f32_e32 v38, v27, v27
	v_mul_f32_e32 v39, v29, v29
	v_fmac_f32_e32 v38, v26, v26
	v_fmac_f32_e32 v39, v28, v28
	v_add_f32_e32 v38, v38, v39
	v_add_f32_e32 v35, v38, v35
	v_mul_f32_e32 v38, v23, v23
	v_mul_f32_e32 v39, v25, v25
	v_fmac_f32_e32 v38, v22, v22
	v_fmac_f32_e32 v39, v24, v24
	v_add_f32_e32 v38, v38, v39
	v_add_f32_e32 v35, v38, v35
	v_mul_f32_e32 v38, v19, v19
	v_mul_f32_e32 v39, v21, v21
	v_fmac_f32_e32 v38, v18, v18
	v_fmac_f32_e32 v39, v20, v20
	v_add_f32_e32 v38, v38, v39
	v_add_f32_e32 v38, v38, v35
	ds_bpermute_b32 v39, v183, v38
	v_pk_mul_f32 v[40:41], v[136:137], v[40:41]
	v_cvt_pk_bf16_f32 v36, v36, v37
	v_cvt_pk_bf16_f32 v35, v40, v41
	v_cvt_pk_bf16_f32 v37, v42, v43
	global_store_dwordx4 v[50:51], v[34:37], off offset:64 sc1 nt
	s_waitcnt lgkmcnt(0)
	s_nop 0
	v_add_f32_e32 v36, v38, v39
	ds_bpermute_b32 v37, v182, v36
	s_cbranch_vccnz .LBB0_305
	v_add_u32_e32 v34, 0xa0, v175
	v_and_b32_e32 v35, s4, v34
	v_lshlrev_b32_e32 v35, s26, v35
	v_ashrrev_i32_e32 v34, s82, v34
	v_add3_u32 v34, v34, s3, v35
	v_ashrrev_i32_e32 v35, 31, v34
	s_add_u32 s12, s98, s0
	s_addc_u32 s13, s99, s1
	v_lshlrev_b64 v[34:35], 8, v[34:35]
	v_lshl_add_u64 v[34:35], s[12:13], 0, v[34:35]
	v_mov_b32_e32 v177, v0
	v_lshl_add_u64 v[34:35], v[34:35], 0, v[176:177]
	s_mov_b64 s[12:13], 0

.LBB0_307:
	s_waitcnt lgkmcnt(0)
	v_add_f32_e32 v36, v36, v37
	v_fmamk_f32 v36, v36, 0x3c800000, v201
	v_rsq_f32_e32 v36, v36
	s_and_b64 vcc, exec, s[38:39]
	s_mov_b64 s[12:13], -1
	v_pk_mul_f32 v[32:33], v[32:33], v[36:37] op_sel_hi:[1,0]
	v_pk_mul_f32 v[30:31], v[30:31], v[36:37] op_sel_hi:[1,0]
	v_pk_mul_f32 v[28:29], v[28:29], v[36:37] op_sel_hi:[1,0]
	v_pk_mul_f32 v[26:27], v[26:27], v[36:37] op_sel_hi:[1,0]
	v_pk_mul_f32 v[32:33], v[144:145], v[32:33]
	v_pk_mul_f32 v[30:31], v[142:143], v[30:31]
	v_pk_mul_f32 v[38:39], v[140:141], v[28:29]
	v_pk_mul_f32 v[28:29], v[138:139], v[26:27]
	v_pk_mul_f32 v[22:23], v[22:23], v[36:37] op_sel_hi:[1,0]
	v_cvt_pk_bf16_f32 v26, v30, v31
	v_cvt_pk_bf16_f32 v27, v32, v33
	v_cvt_pk_bf16_f32 v28, v28, v29
	v_cvt_pk_bf16_f32 v29, v38, v39
	v_pk_mul_f32 v[22:23], v[134:135], v[22:23]
	v_pk_mul_f32 v[20:21], v[20:21], v[36:37] op_sel_hi:[1,0]
	v_pk_mul_f32 v[18:19], v[18:19], v[36:37] op_sel_hi:[1,0]
	global_store_dwordx4 v[34:35], v[26:29], off sc1 nt
	v_pk_mul_f32 v[24:25], v[24:25], v[36:37] op_sel_hi:[1,0]
	s_nop 0
	v_pk_mul_f32 v[26:27], v[132:133], v[20:21]
	v_pk_mul_f32 v[20:21], v[130:131], v[18:19]
	v_cvt_pk_bf16_f32 v18, v22, v23
	v_mul_f32_e32 v19, v15, v15
	v_mul_f32_e32 v22, v17, v17
	v_fmac_f32_e32 v19, v14, v14
	v_fmac_f32_e32 v22, v16, v16
	v_add_f32_e32 v19, v19, v22
	v_mul_f32_e32 v22, v11, v11
	v_mul_f32_e32 v23, v13, v13
	v_fmac_f32_e32 v22, v10, v10
	v_fmac_f32_e32 v23, v12, v12
	v_add_f32_e32 v22, v22, v23
	v_add_f32_e32 v19, v22, v19
	v_mul_f32_e32 v22, v7, v7
	v_mul_f32_e32 v23, v9, v9
	v_fmac_f32_e32 v22, v6, v6
	v_fmac_f32_e32 v23, v8, v8
	v_add_f32_e32 v22, v22, v23
	v_add_f32_e32 v19, v22, v19
	v_mul_f32_e32 v22, v3, v3
	v_mul_f32_e32 v23, v5, v5
	v_fmac_f32_e32 v22, v2, v2
	v_fmac_f32_e32 v23, v4, v4
	v_add_f32_e32 v22, v22, v23
	v_add_f32_e32 v22, v22, v19
	ds_bpermute_b32 v23, v183, v22
	v_pk_mul_f32 v[24:25], v[136:137], v[24:25]
	v_cvt_pk_bf16_f32 v20, v20, v21
	v_cvt_pk_bf16_f32 v19, v24, v25
	v_cvt_pk_bf16_f32 v21, v26, v27
	global_store_dwordx4 v[34:35], v[18:21], off offset:64 sc1 nt
	s_waitcnt lgkmcnt(0)
	s_nop 0
	v_add_f32_e32 v20, v22, v23
	ds_bpermute_b32 v21, v182, v20
	s_cbranch_vccnz .LBB0_309
	v_add_u32_e32 v18, 0xb0, v175
	v_and_b32_e32 v19, s4, v18
	v_lshlrev_b32_e32 v19, s26, v19
	v_ashrrev_i32_e32 v18, s82, v18
	v_add3_u32 v18, v18, s3, v19
	v_ashrrev_i32_e32 v19, 31, v18
	s_add_u32 s0, s98, s0
	s_addc_u32 s1, s99, s1
	v_lshlrev_b64 v[18:19], 8, v[18:19]
	v_lshl_add_u64 v[18:19], s[0:1], 0, v[18:19]
	v_mov_b32_e32 v177, v0
	v_lshl_add_u64 v[18:19], v[18:19], 0, v[176:177]
	s_mov_b64 s[12:13], 0

.LBB0_311:
	s_waitcnt lgkmcnt(0)
	v_add_f32_e32 v20, v20, v21
	v_fmamk_f32 v20, v20, 0x3c800000, v201
	v_rsq_f32_e32 v20, v20
	s_nop 0
	v_pk_mul_f32 v[16:17], v[16:17], v[20:21] op_sel_hi:[1,0]
	v_pk_mul_f32 v[14:15], v[14:15], v[20:21] op_sel_hi:[1,0]
	v_pk_mul_f32 v[12:13], v[12:13], v[20:21] op_sel_hi:[1,0]
	v_pk_mul_f32 v[10:11], v[10:11], v[20:21] op_sel_hi:[1,0]
	v_pk_mul_f32 v[16:17], v[144:145], v[16:17]
	v_pk_mul_f32 v[14:15], v[142:143], v[14:15]
	v_pk_mul_f32 v[22:23], v[140:141], v[12:13]
	v_pk_mul_f32 v[12:13], v[138:139], v[10:11]
	v_cvt_pk_bf16_f32 v10, v14, v15
	v_cvt_pk_bf16_f32 v11, v16, v17
	v_cvt_pk_bf16_f32 v12, v12, v13
	v_cvt_pk_bf16_f32 v13, v22, v23
	v_pk_mul_f32 v[8:9], v[8:9], v[20:21] op_sel_hi:[1,0]
	v_pk_mul_f32 v[6:7], v[6:7], v[20:21] op_sel_hi:[1,0]
	v_pk_mul_f32 v[4:5], v[4:5], v[20:21] op_sel_hi:[1,0]
	v_pk_mul_f32 v[2:3], v[2:3], v[20:21] op_sel_hi:[1,0]
	global_store_dwordx4 v[18:19], v[10:13], off sc1 nt
	v_pk_mul_f32 v[8:9], v[136:137], v[8:9]
	v_pk_mul_f32 v[6:7], v[134:135], v[6:7]
	v_pk_mul_f32 v[10:11], v[132:133], v[4:5]
	v_pk_mul_f32 v[4:5], v[130:131], v[2:3]
	v_cvt_pk_bf16_f32 v2, v6, v7
	v_cvt_pk_bf16_f32 v3, v8, v9
	v_cvt_pk_bf16_f32 v4, v4, v5
	v_cvt_pk_bf16_f32 v5, v10, v11
	global_store_dwordx4 v[18:19], v[2:5], off offset:64 sc1 nt
	s_and_b64 vcc, exec, s[36:37]
	s_mov_b64 s[0:1], -1
	s_cbranch_vccnz .LBB0_259
